# P2b rewritten (batched loads, 12B/lane) + GEMM K-loops: counted vmcnt for true 2-deep register prefetch
# speedup vs baseline: 1.0189x; 1.0189x over previous
.LBB0_160:
	s_setprio 1
	ds_read_b128 v[192:195], v180 offset:2560
	ds_read_b128 v[196:199], v180
	ds_read_b128 v[204:207], v189 offset:20480
	ds_read_b128 v[200:203], v180 offset:32
	s_waitcnt lgkmcnt(1)
	v_mfma_f32_32x32x16_bf16 v[112:127], v[196:199], v[204:207], v[112:127]
	ds_read_b128 v[208:211], v189 offset:20512
	v_mfma_f32_32x32x16_bf16 v[80:95], v[192:195], v[204:207], v[80:95]
	ds_read_b128 v[204:207], v189 offset:23040
	s_waitcnt lgkmcnt(0)
	v_mfma_f32_32x32x16_bf16 v[96:111], v[196:199], v[204:207], v[96:111]
	v_mfma_f32_32x32x16_bf16 v[64:79], v[192:195], v[204:207], v[64:79]
	ds_read_b128 v[204:207], v189 offset:25600
	s_waitcnt lgkmcnt(0)
	v_mfma_f32_32x32x16_bf16 v[48:63], v[196:199], v[204:207], v[48:63]
	v_mfma_f32_32x32x16_bf16 v[16:31], v[192:195], v[204:207], v[16:31]
	ds_read_b128 v[204:207], v189 offset:28160
	s_waitcnt lgkmcnt(0)
	v_mfma_f32_32x32x16_bf16 v[32:47], v[196:199], v[204:207], v[32:47]
	ds_read_b128 v[196:199], v189 offset:23072
	v_mfma_f32_32x32x16_bf16 v[0:15], v[192:195], v[204:207], v[0:15]
	ds_read_b128 v[192:195], v180 offset:2592
	v_mfma_f32_32x32x16_bf16 v[112:127], v[200:203], v[208:211], v[112:127]
	s_waitcnt lgkmcnt(0)
	v_mfma_f32_32x32x16_bf16 v[80:95], v[192:195], v[208:211], v[80:95]
	v_mfma_f32_32x32x16_bf16 v[96:111], v[200:203], v[196:199], v[96:111]
	v_mfma_f32_32x32x16_bf16 v[64:79], v[192:195], v[196:199], v[64:79]
	ds_read_b128 v[196:199], v189 offset:25632
	s_waitcnt lgkmcnt(0)
	v_mfma_f32_32x32x16_bf16 v[48:63], v[200:203], v[196:199], v[48:63]
	v_mfma_f32_32x32x16_bf16 v[16:31], v[192:195], v[196:199], v[16:31]
	ds_read_b128 v[196:199], v189 offset:28192
	s_waitcnt lgkmcnt(0)
	v_mfma_f32_32x32x16_bf16 v[32:47], v[200:203], v[196:199], v[32:47]
	v_mfma_f32_32x32x16_bf16 v[0:15], v[192:195], v[196:199], v[0:15]
	s_setprio 0
	s_cmp_gt_u32 s8, 28
	s_cbranch_scc1 .Lvt_0
	s_waitcnt vmcnt(11)
	ds_write_b128 v187, v[148:151] offset:10240
	s_waitcnt vmcnt(10)
	ds_write_b128 v187, v[156:159] offset:15360
	s_waitcnt vmcnt(9)
	ds_write_b128 v187, v[160:163] offset:40960
	s_waitcnt vmcnt(8)
	ds_write_b128 v187, v[164:167] offset:46080
	s_waitcnt vmcnt(7)
	ds_write_b128 v187, v[168:171] offset:51200
	s_waitcnt vmcnt(6)
	ds_write_b128 v187, v[172:175] offset:56320
	s_branch .Lvj_0
.Lvt_0:
	s_waitcnt vmcnt(5)
	ds_write_b128 v187, v[148:151] offset:10240
	s_waitcnt vmcnt(4)
	ds_write_b128 v187, v[156:159] offset:15360
	s_waitcnt vmcnt(3)
	ds_write_b128 v187, v[160:163] offset:40960
	s_waitcnt vmcnt(2)
	ds_write_b128 v187, v[164:167] offset:46080
	s_waitcnt vmcnt(1)
	ds_write_b128 v187, v[168:171] offset:51200
	s_waitcnt vmcnt(0)
	ds_write_b128 v187, v[172:175] offset:56320
.Lvj_0:
	s_waitcnt lgkmcnt(0)
	s_barrier
	s_cbranch_scc1 .LBB0_162
	v_add_u32_e32 v148, 0xc0, v191
	v_add_u32_e32 v156, 0x200c0, v191
	v_lshl_add_u64 v[160:161], v[182:183], 0, s[2:3]
	v_add_u32_e32 v164, 0x200c0, v190
	v_add_u32_e32 v168, 0x400c0, v190
	v_add_u32_e32 v172, 0x600c0, v190
	global_load_dwordx4 v[148:151], v148, s[22:23]
	s_nop 0
	global_load_dwordx4 v[156:159], v156, s[22:23]
	s_nop 0
	global_load_dwordx4 v[160:163], v[160:161], off
	s_nop 0
	global_load_dwordx4 v[164:167], v164, s[24:25]
	s_nop 0
	global_load_dwordx4 v[168:171], v168, s[24:25]
	s_nop 0
	global_load_dwordx4 v[172:175], v172, s[24:25]
.LBB0_162:
	s_setprio 1
	ds_read_b128 v[190:193], v180 offset:12800
	ds_read_b128 v[194:197], v180 offset:10240
	ds_read_b128 v[202:205], v189 offset:40960
	ds_read_b128 v[198:201], v180 offset:10272
	s_waitcnt lgkmcnt(1)
	v_mfma_f32_32x32x16_bf16 v[112:127], v[194:197], v[202:205], v[112:127]
	ds_read_b128 v[206:209], v189 offset:40992
	v_mfma_f32_32x32x16_bf16 v[80:95], v[190:193], v[202:205], v[80:95]
	ds_read_b128 v[202:205], v189 offset:43520
	s_waitcnt lgkmcnt(0)
	v_mfma_f32_32x32x16_bf16 v[96:111], v[194:197], v[202:205], v[96:111]
	v_mfma_f32_32x32x16_bf16 v[64:79], v[190:193], v[202:205], v[64:79]
	ds_read_b128 v[202:205], v189 offset:46080
	s_waitcnt lgkmcnt(0)
	v_mfma_f32_32x32x16_bf16 v[48:63], v[194:197], v[202:205], v[48:63]
	v_mfma_f32_32x32x16_bf16 v[16:31], v[190:193], v[202:205], v[16:31]
	ds_read_b128 v[202:205], v189 offset:48640
	s_waitcnt lgkmcnt(0)
	v_mfma_f32_32x32x16_bf16 v[32:47], v[194:197], v[202:205], v[32:47]
	ds_read_b128 v[194:197], v189 offset:43552
	v_mfma_f32_32x32x16_bf16 v[0:15], v[190:193], v[202:205], v[0:15]
	ds_read_b128 v[190:193], v180 offset:12832
	v_mfma_f32_32x32x16_bf16 v[112:127], v[198:201], v[206:209], v[112:127]
	s_waitcnt lgkmcnt(0)
	v_mfma_f32_32x32x16_bf16 v[80:95], v[190:193], v[206:209], v[80:95]
	v_mfma_f32_32x32x16_bf16 v[96:111], v[198:201], v[194:197], v[96:111]
	v_mfma_f32_32x32x16_bf16 v[64:79], v[190:193], v[194:197], v[64:79]
	ds_read_b128 v[194:197], v189 offset:46112
	s_waitcnt lgkmcnt(0)
	v_mfma_f32_32x32x16_bf16 v[48:63], v[198:201], v[194:197], v[48:63]
	v_mfma_f32_32x32x16_bf16 v[16:31], v[190:193], v[194:197], v[16:31]
	ds_read_b128 v[194:197], v189 offset:48672
	s_waitcnt lgkmcnt(0)
	v_mfma_f32_32x32x16_bf16 v[32:47], v[198:201], v[194:197], v[32:47]
	v_mfma_f32_32x32x16_bf16 v[0:15], v[190:193], v[194:197], v[0:15]
	s_setprio 0
	s_andn2_b64 vcc, exec, s[6:7]
	s_cbranch_vccnz .LBB0_157
	s_waitcnt vmcnt(11)
	ds_write_b128 v187, v[128:131]
	s_waitcnt vmcnt(10)
	ds_write_b128 v187, v[132:135] offset:5120
	s_waitcnt vmcnt(9)
	ds_write_b128 v187, v[136:139] offset:20480
	s_waitcnt vmcnt(8)
	ds_write_b128 v187, v[140:143] offset:25600
	s_waitcnt vmcnt(7)
	ds_write_b128 v187, v[144:147] offset:30720
	s_waitcnt vmcnt(6)
	ds_write_b128 v187, v[152:155] offset:35840
	s_branch .LBB0_157

.LBB0_181:
	s_setprio 1
	ds_read_b128 v[146:149], v132 offset:4608
	ds_read_b128 v[150:153], v133 offset:41472
	s_waitcnt lgkmcnt(0)
	v_mfma_f32_32x32x16_bf16 v[0:15], v[146:149], v[150:153], v[0:15]
	ds_read_b128 v[154:157], v132
	ds_read_b128 v[158:161], v132 offset:32
	s_waitcnt lgkmcnt(1)
	v_mfma_f32_32x32x16_bf16 v[32:47], v[154:157], v[150:153], v[32:47]
	ds_read_b128 v[162:165], v133 offset:36864
	ds_read_b128 v[166:169], v133 offset:36896
	s_waitcnt lgkmcnt(1)
	v_mfma_f32_32x32x16_bf16 v[48:63], v[154:157], v[162:165], v[48:63]
	ds_read_b128 v[150:153], v133 offset:41504
	ds_read_b128 v[154:157], v133 offset:36928
	v_mfma_f32_32x32x16_bf16 v[16:31], v[146:149], v[162:165], v[16:31]
	ds_read_b128 v[146:149], v132 offset:4640
	s_waitcnt lgkmcnt(3)
	v_mfma_f32_32x32x16_bf16 v[48:63], v[158:161], v[166:169], v[48:63]
	s_waitcnt lgkmcnt(2)
	v_mfma_f32_32x32x16_bf16 v[32:47], v[158:161], v[150:153], v[32:47]
	ds_read_b128 v[158:161], v133 offset:41536
	s_waitcnt lgkmcnt(1)
	v_mfma_f32_32x32x16_bf16 v[16:31], v[146:149], v[166:169], v[16:31]
	v_mfma_f32_32x32x16_bf16 v[0:15], v[146:149], v[150:153], v[0:15]
	ds_read_b128 v[146:149], v132 offset:64
	ds_read_b128 v[150:153], v132 offset:4672
	s_waitcnt lgkmcnt(1)
	v_mfma_f32_32x32x16_bf16 v[48:63], v[146:149], v[154:157], v[48:63]
	v_mfma_f32_32x32x16_bf16 v[32:47], v[146:149], v[158:161], v[32:47]
	ds_read_b128 v[146:149], v132 offset:96
	s_waitcnt lgkmcnt(1)
	v_mfma_f32_32x32x16_bf16 v[16:31], v[150:153], v[154:157], v[16:31]
	ds_read_b128 v[154:157], v133 offset:36960
	v_mfma_f32_32x32x16_bf16 v[0:15], v[150:153], v[158:161], v[0:15]
	ds_read_b128 v[150:153], v132 offset:4704
	ds_read_b128 v[158:161], v133 offset:41568
	s_waitcnt lgkmcnt(2)
	v_mfma_f32_32x32x16_bf16 v[48:63], v[146:149], v[154:157], v[48:63]
	s_waitcnt lgkmcnt(0)
	v_mfma_f32_32x32x16_bf16 v[32:47], v[146:149], v[158:161], v[32:47]
	v_mfma_f32_32x32x16_bf16 v[16:31], v[150:153], v[154:157], v[16:31]
	v_mfma_f32_32x32x16_bf16 v[0:15], v[150:153], v[158:161], v[0:15]
	s_setprio 0
	s_cmp_gt_u32 s8, 12
	s_cbranch_scc1 .Lvt_1
	s_waitcnt vmcnt(15)
	ds_write_b128 v130, v[92:95] offset:18432
	s_waitcnt vmcnt(14)
	ds_write_b128 v130, v[96:99] offset:55296
	s_waitcnt vmcnt(13)
	ds_write_b128 v130, v[104:107] offset:23040
	s_waitcnt vmcnt(12)
	ds_write_b128 v130, v[108:111] offset:59904
	s_waitcnt vmcnt(11)
	ds_write_b128 v130, v[112:115] offset:27648
	s_waitcnt vmcnt(10)
	ds_write_b128 v130, v[116:119] offset:64512
	s_waitcnt vmcnt(9)
	ds_write_b128 v130, v[120:123] offset:32256
	s_waitcnt vmcnt(8)
	ds_write_b128 v144, v[124:127] offset:13824
	s_branch .Lvj_1
.Lvt_1:
	s_waitcnt vmcnt(7)
	ds_write_b128 v130, v[92:95] offset:18432
	s_waitcnt vmcnt(6)
	ds_write_b128 v130, v[96:99] offset:55296
	s_waitcnt vmcnt(5)
	ds_write_b128 v130, v[104:107] offset:23040
	s_waitcnt vmcnt(4)
	ds_write_b128 v130, v[108:111] offset:59904
	s_waitcnt vmcnt(3)
	ds_write_b128 v130, v[112:115] offset:27648
	s_waitcnt vmcnt(2)
	ds_write_b128 v130, v[116:119] offset:64512
	s_waitcnt vmcnt(1)
	ds_write_b128 v130, v[120:123] offset:32256
	s_waitcnt vmcnt(0)
	ds_write_b128 v144, v[124:127] offset:13824
.Lvj_1:
	s_waitcnt lgkmcnt(0)
	s_barrier
	s_cbranch_scc1 .LBB0_183
	v_add_u32_e32 v92, 0x180, v145
	v_lshl_add_u64 v[96:97], v[140:141], 0, s[0:1]
	v_add_u32_e32 v104, 0x10180, v145
	v_lshl_add_u64 v[108:109], v[138:139], 0, s[0:1]
	v_add_u32_e32 v112, 0x20180, v145
	v_lshl_add_u64 v[116:117], v[136:137], 0, s[0:1]
	v_add_u32_e32 v120, 0x30180, v145
	v_lshl_add_u64 v[124:125], v[134:135], 0, s[0:1]
	global_load_dwordx4 v[92:95], v92, s[12:13]
	s_nop 0
	global_load_dwordx4 v[96:99], v[96:97], off
	s_nop 0
	global_load_dwordx4 v[104:107], v104, s[12:13]
	s_nop 0
	global_load_dwordx4 v[108:111], v[108:109], off
	s_nop 0
	global_load_dwordx4 v[112:115], v112, s[12:13]
	s_nop 0
	global_load_dwordx4 v[116:119], v[116:117], off
	s_nop 0
	global_load_dwordx4 v[120:123], v120, s[12:13]
	s_nop 0
	global_load_dwordx4 v[124:127], v[124:125], off
.LBB0_183:
	s_setprio 1
	ds_read_b128 v[146:149], v132 offset:23040
	ds_read_b128 v[150:153], v133 offset:59904
	s_waitcnt lgkmcnt(0)
	v_mfma_f32_32x32x16_bf16 v[0:15], v[146:149], v[150:153], v[0:15]
	ds_read_b128 v[154:157], v132 offset:18432
	ds_read_b128 v[158:161], v132 offset:18464
	s_waitcnt lgkmcnt(1)
	v_mfma_f32_32x32x16_bf16 v[32:47], v[154:157], v[150:153], v[32:47]
	ds_read_b128 v[162:165], v133 offset:55296
	ds_read_b128 v[166:169], v133 offset:55328
	s_waitcnt lgkmcnt(1)
	v_mfma_f32_32x32x16_bf16 v[48:63], v[154:157], v[162:165], v[48:63]
	ds_read_b128 v[150:153], v133 offset:59936
	ds_read_b128 v[154:157], v133 offset:55360
	v_mfma_f32_32x32x16_bf16 v[16:31], v[146:149], v[162:165], v[16:31]
	ds_read_b128 v[146:149], v132 offset:23072
	s_waitcnt lgkmcnt(3)
	v_mfma_f32_32x32x16_bf16 v[48:63], v[158:161], v[166:169], v[48:63]
	s_waitcnt lgkmcnt(2)
	v_mfma_f32_32x32x16_bf16 v[32:47], v[158:161], v[150:153], v[32:47]
	ds_read_b128 v[158:161], v133 offset:59968
	s_waitcnt lgkmcnt(1)
	v_mfma_f32_32x32x16_bf16 v[16:31], v[146:149], v[166:169], v[16:31]
	v_mfma_f32_32x32x16_bf16 v[0:15], v[146:149], v[150:153], v[0:15]
	ds_read_b128 v[146:149], v132 offset:18496
	ds_read_b128 v[150:153], v132 offset:23104
	s_waitcnt lgkmcnt(1)
	v_mfma_f32_32x32x16_bf16 v[48:63], v[146:149], v[154:157], v[48:63]
	v_mfma_f32_32x32x16_bf16 v[32:47], v[146:149], v[158:161], v[32:47]
	ds_read_b128 v[146:149], v132 offset:18528
	s_waitcnt lgkmcnt(1)
	v_mfma_f32_32x32x16_bf16 v[16:31], v[150:153], v[154:157], v[16:31]
	ds_read_b128 v[154:157], v133 offset:55392
	v_mfma_f32_32x32x16_bf16 v[0:15], v[150:153], v[158:161], v[0:15]
	ds_read_b128 v[150:153], v132 offset:23136
	ds_read_b128 v[158:161], v133 offset:60000
	s_waitcnt lgkmcnt(2)
	v_mfma_f32_32x32x16_bf16 v[48:63], v[146:149], v[154:157], v[48:63]
	s_waitcnt lgkmcnt(0)
	v_mfma_f32_32x32x16_bf16 v[32:47], v[146:149], v[158:161], v[32:47]
	v_mfma_f32_32x32x16_bf16 v[16:31], v[150:153], v[154:157], v[16:31]
	v_mfma_f32_32x32x16_bf16 v[0:15], v[150:153], v[158:161], v[0:15]
	s_setprio 0
	s_andn2_b64 vcc, exec, s[4:5]
	s_cbranch_vccnz .LBB0_178
	s_waitcnt vmcnt(15)
	ds_write_b128 v130, v[64:67]
	s_waitcnt vmcnt(14)
	ds_write_b128 v130, v[68:71] offset:36864
	s_waitcnt vmcnt(13)
	ds_write_b128 v130, v[72:75] offset:4608
	s_waitcnt vmcnt(12)
	ds_write_b128 v130, v[76:79] offset:41472
	s_waitcnt vmcnt(11)
	ds_write_b128 v130, v[80:83] offset:9216
	s_waitcnt vmcnt(10)
	ds_write_b128 v130, v[84:87] offset:46080
	s_waitcnt vmcnt(9)
	ds_write_b128 v130, v[88:91] offset:13824
	s_waitcnt vmcnt(8)
	ds_write_b128 v130, v[100:103] offset:50688
	s_branch .LBB0_178

.LBB0_573:
	s_or_b64 exec, exec, s[0:1]
	v_mov_b32_e32 v0, v216
	v_readlane_b32 s0, v254, 45
	s_barrier
	v_readlane_b32 s6, v254, 51
	v_ashrrev_i32_e32 v1, 6, v0
	v_readlane_b32 s7, v254, 52
	v_add_u32_e32 v34, s55, v1
	v_readlane_b32 s2, v254, 47
	v_readlane_b32 s3, v254, 48
	v_mov_b32_e32 v1, s6
	v_mov_b32_e32 v2, s7
	v_readlane_b32 s1, v254, 46
	v_cmp_gt_i32_e32 vcc, s45, v34
	v_readfirstlane_b32 s2, v1
	v_readfirstlane_b32 s3, v2
	v_readlane_b32 s4, v254, 49
	v_readlane_b32 s5, v254, 50
	s_and_saveexec_b64 s[0:1], vcc
	s_cbranch_execz .LBB0_592
	v_readlane_b32 s6, v255, 44
	v_readlane_b32 s22, v255, 12
	v_readlane_b32 s23, v255, 13
	s_mul_i32 s6, s6, 0x180
	s_add_u32 s22, s22, s6
	s_addc_u32 s23, s23, 0
	v_and_b32_e32 v0, 63, v216
	v_and_b32_e32 v6, 15, v0
	v_mul_u32_u24_e32 v6, 24, v6
	v_mul_u32_u24_e32 v1, 12, v0
	v_mul_u32_u24_e32 v2, 24, v0
	v_mul_u32_u24_e32 v3, 6, v0
	global_load_dwordx4 v[8:11], v6, s[22:23]
	global_load_dwordx2 v[12:13], v6, s[22:23] offset:16
	s_add_u32 s4, s2, 0x18f80000
	s_addc_u32 s5, s3, 0
	s_add_u32 s6, s4, 0x80000
	s_addc_u32 s7, s5, 0
	s_add_u32 s8, s4, 0x100000
	s_addc_u32 s9, s5, 0
	s_add_u32 s10, s2, 0x24a22100
	s_addc_u32 s11, s3, 0
	s_add_u32 s12, s10, 0xc00000
	s_addc_u32 s13, s11, 0
	s_add_u32 s14, s10, 0x1800000
	s_addc_u32 s15, s11, 0
	s_add_u32 s16, s2, 0x26e22100
	s_addc_u32 s17, s3, 0
	s_add_u32 s18, s2, 0x22622700
	s_addc_u32 s19, s3, 0
	s_add_u32 s20, s2, 0x28622100
	s_addc_u32 s21, s3, 0
	v_lshrrev_b32_e32 v4, 6, v3
	v_add_u32_e32 v5, 5, v3
	v_lshrrev_b32_e32 v5, 6, v5
	v_lshlrev_b32_e32 v4, 2, v4
	v_lshlrev_b32_e32 v5, 2, v5
	v_and_b32_e32 v3, 63, v3
	v_sub_u32_e32 v3, 64, v3
	v_min_u32_e32 v3, 6, v3
	v_mov_b32_e32 v7, 0x3727c5ac
	v_readfirstlane_b32 s22, v34
.Lp2b_loop:
	s_lshl_b32 s2, s22, 5
	s_mul_i32 s3, s22, 0x300
	v_add_u32_e32 v14, s2, v4
	v_add_u32_e32 v15, s2, v5
	v_add_u32_e32 v16, s3, v1
	s_mul_i32 s2, s22, 0x600
	s_mul_i32 s3, s22, 0x900
	v_add_u32_e32 v17, s2, v2
	v_add_u32_e32 v18, s3, v1
	s_lshl_b32 s2, s22, 11
	v_add_u32_e32 v19, s2, v1
	global_load_dword v20, v14, s[4:5]
	global_load_dword v21, v14, s[6:7]
	global_load_dword v22, v14, s[8:9]
	global_load_dword v23, v15, s[4:5]
	global_load_dword v24, v15, s[6:7]
	global_load_dword v25, v15, s[8:9]
	global_load_dwordx3 v[26:28], v16, s[10:11]
	global_load_dwordx3 v[30:32], v16, s[12:13]
	global_load_dwordx3 v[76:78], v16, s[14:15]
	global_load_dwordx4 v[36:39], v17, s[16:17]
	global_load_dwordx2 v[40:41], v17, s[16:17] offset:16
	global_load_dwordx3 v[42:44], v18, s[18:19]
	s_waitcnt vmcnt(6)
	v_max3_f32 v45, v20, v21, v22
	v_max3_f32 v46, v23, v24, v25
	v_sub_f32_e32 v20, v20, v45
	v_sub_f32_e32 v21, v21, v45
	v_sub_f32_e32 v22, v22, v45
	v_sub_f32_e32 v23, v23, v46
	v_sub_f32_e32 v24, v24, v46
	v_sub_f32_e32 v25, v25, v46
	v_mul_f32_e32 v20, 0x3fb8aa3b, v20
	v_mul_f32_e32 v21, 0x3fb8aa3b, v21
	v_mul_f32_e32 v22, 0x3fb8aa3b, v22
	v_mul_f32_e32 v23, 0x3fb8aa3b, v23
	v_mul_f32_e32 v24, 0x3fb8aa3b, v24
	v_mul_f32_e32 v25, 0x3fb8aa3b, v25
	v_exp_f32_e32 v20, v20
	v_exp_f32_e32 v21, v21
	v_exp_f32_e32 v22, v22
	v_exp_f32_e32 v23, v23
	v_exp_f32_e32 v24, v24
	v_exp_f32_e32 v25, v25
	s_nop 0
	v_add_f32_e32 v45, v20, v21
	v_add_f32_e32 v46, v23, v24
	v_add_f32_e32 v45, v45, v22
	v_add_f32_e32 v46, v46, v25
	v_rcp_f32_e32 v45, v45
	v_rcp_f32_e32 v46, v46
	v_cmp_ge_u32_e32 vcc, 2, v3
	v_cmp_ge_u32_e64 s[2:3], 4, v3
	v_mul_f32_e32 v20, v20, v45
	v_mul_f32_e32 v21, v21, v45
	v_mul_f32_e32 v22, v22, v45
	v_mul_f32_e32 v23, v23, v46
	v_mul_f32_e32 v24, v24, v46
	v_mul_f32_e32 v25, v25, v46
	s_nop 0
	v_cndmask_b32_e32 v46, v20, v23, vcc
	v_cndmask_b32_e32 v47, v21, v24, vcc
	v_cndmask_b32_e32 v48, v22, v25, vcc
	v_cndmask_b32_e64 v49, v20, v23, s[2:3]
	v_cndmask_b32_e64 v50, v21, v24, s[2:3]
	v_cndmask_b32_e64 v51, v22, v25, s[2:3]
	s_waitcnt vmcnt(3)
	v_lshlrev_b32_e32 v55, 16, v26
	v_lshlrev_b32_e32 v56, 16, v30
	v_lshlrev_b32_e32 v57, 16, v76
	v_and_b32_e32 v58, 0xffff0000, v26
	v_and_b32_e32 v59, 0xffff0000, v30
	v_and_b32_e32 v60, 0xffff0000, v76
	v_mul_f32_e32 v55, v20, v55
	v_mul_f32_e32 v58, v20, v58
	v_fmac_f32_e32 v55, v21, v56
	v_fmac_f32_e32 v58, v21, v59
	v_fmac_f32_e32 v55, v22, v57
	v_fmac_f32_e32 v58, v22, v60
	v_cvt_pk_bf16_f32 v52, v55, v58
	v_lshlrev_b32_e32 v55, 16, v27
	v_lshlrev_b32_e32 v56, 16, v31
	v_lshlrev_b32_e32 v57, 16, v77
	v_and_b32_e32 v58, 0xffff0000, v27
	v_and_b32_e32 v59, 0xffff0000, v31
	v_and_b32_e32 v60, 0xffff0000, v77
	v_mul_f32_e32 v55, v46, v55
	v_mul_f32_e32 v58, v46, v58
	v_fmac_f32_e32 v55, v47, v56
	v_fmac_f32_e32 v58, v47, v59
	v_fmac_f32_e32 v55, v48, v57
	v_fmac_f32_e32 v58, v48, v60
	v_cvt_pk_bf16_f32 v53, v55, v58
	v_lshlrev_b32_e32 v55, 16, v28
	v_lshlrev_b32_e32 v56, 16, v32
	v_lshlrev_b32_e32 v57, 16, v78
	v_and_b32_e32 v58, 0xffff0000, v28
	v_and_b32_e32 v59, 0xffff0000, v32
	v_and_b32_e32 v60, 0xffff0000, v78
	v_mul_f32_e32 v55, v49, v55
	v_mul_f32_e32 v58, v49, v58
	v_fmac_f32_e32 v55, v50, v56
	v_fmac_f32_e32 v58, v50, v59
	v_fmac_f32_e32 v55, v51, v57
	v_fmac_f32_e32 v58, v51, v60
	v_cvt_pk_bf16_f32 v54, v55, v58
	s_nop 0
	global_store_dwordx3 v19, v[52:54], s[20:21] offset:512
	s_waitcnt vmcnt(1)
	v_mul_f32_e32 v45, v36, v36
	v_fmac_f32_e32 v45, v37, v37
	v_fmac_f32_e32 v45, v38, v38
	v_fmac_f32_e32 v45, v39, v39
	v_fmac_f32_e32 v45, v40, v40
	v_fmac_f32_e32 v45, v41, v41
	v_lshlrev_b32_e32 v61, 16, v42
	v_and_b32_e32 v62, 0xffff0000, v42
	v_add_f32_dpp v46, v45, v45 row_ror:8 row_mask:0xf bank_mask:0xf
	v_lshlrev_b32_e32 v63, 16, v43
	v_and_b32_e32 v64, 0xffff0000, v43
	v_add_f32_dpp v47, v46, v46 row_ror:4 row_mask:0xf bank_mask:0xf
	v_lshlrev_b32_e32 v65, 16, v44
	v_and_b32_e32 v66, 0xffff0000, v44
	v_add_f32_dpp v48, v47, v47 row_ror:2 row_mask:0xf bank_mask:0xf
	v_mul_f32_e32 v67, 0xbfb8aa3b, v61
	v_mul_f32_e32 v68, 0xbfb8aa3b, v62
	v_add_f32_dpp v49, v48, v48 row_ror:1 row_mask:0xf bank_mask:0xf
	v_mul_f32_e32 v69, 0xbfb8aa3b, v63
	v_mul_f32_e32 v70, 0xbfb8aa3b, v64
	v_mul_f32_e32 v71, 0xbfb8aa3b, v65
	v_mul_f32_e32 v72, 0xbfb8aa3b, v66
	v_fmamk_f32 v49, v49, 0x3c2aaaab, v7
	v_exp_f32_e32 v67, v67
	v_exp_f32_e32 v68, v68
	v_exp_f32_e32 v69, v69
	v_exp_f32_e32 v70, v70
	v_exp_f32_e32 v71, v71
	v_exp_f32_e32 v72, v72
	v_rsq_f32_e32 v49, v49
	v_add_f32_e32 v67, 1.0, v67
	v_add_f32_e32 v68, 1.0, v68
	v_add_f32_e32 v69, 1.0, v69
	v_add_f32_e32 v70, 1.0, v70
	v_add_f32_e32 v71, 1.0, v71
	v_add_f32_e32 v72, 1.0, v72
	v_rcp_f32_e32 v67, v67
	v_rcp_f32_e32 v68, v68
	v_rcp_f32_e32 v69, v69
	v_rcp_f32_e32 v70, v70
	v_rcp_f32_e32 v71, v71
	v_rcp_f32_e32 v72, v72
	v_mul_f32_e32 v36, v36, v49
	v_mul_f32_e32 v37, v37, v49
	v_mul_f32_e32 v38, v38, v49
	v_mul_f32_e32 v39, v39, v49
	v_mul_f32_e32 v40, v40, v49
	v_mul_f32_e32 v41, v41, v49
	v_mul_f32_e32 v61, v61, v67
	v_mul_f32_e32 v62, v62, v68
	v_mul_f32_e32 v63, v63, v69
	v_mul_f32_e32 v64, v64, v70
	v_mul_f32_e32 v65, v65, v71
	v_mul_f32_e32 v66, v66, v72
	v_mul_f32_e32 v36, v36, v8
	v_mul_f32_e32 v37, v37, v9
	v_mul_f32_e32 v38, v38, v10
	v_mul_f32_e32 v39, v39, v11
	v_mul_f32_e32 v40, v40, v12
	v_mul_f32_e32 v41, v41, v13
	v_mul_f32_e32 v36, v36, v61
	v_mul_f32_e32 v37, v37, v62
	v_mul_f32_e32 v38, v38, v63
	v_mul_f32_e32 v39, v39, v64
	v_mul_f32_e32 v40, v40, v65
	v_mul_f32_e32 v41, v41, v66
	v_cvt_pk_bf16_f32 v80, v36, v37
	v_cvt_pk_bf16_f32 v81, v38, v39
	v_cvt_pk_bf16_f32 v82, v40, v41
	s_add_i32 s22, s22, s50
	s_cmp_lt_i32 s22, 0x4000
	global_store_dwordx3 v19, v[80:82], s[20:21] offset:1280
	s_cbranch_scc1 .Lp2b_loop

.LBB0_628:
	s_setprio 1
	ds_read_b128 v[146:149], v135 offset:41472
	ds_read_b128 v[142:145], v134 offset:4608
	s_waitcnt lgkmcnt(0)
	v_mfma_f32_32x32x16_bf16 v[0:15], v[146:149], v[142:145], v[0:15]
	ds_read_b128 v[150:153], v134
	ds_read_b128 v[154:157], v134 offset:32
	s_waitcnt lgkmcnt(1)
	v_mfma_f32_32x32x16_bf16 v[32:47], v[146:149], v[150:153], v[32:47]
	ds_read_b128 v[158:161], v135 offset:36864
	ds_read_b128 v[162:165], v135 offset:36896
	s_waitcnt lgkmcnt(1)
	v_mfma_f32_32x32x16_bf16 v[48:63], v[158:161], v[150:153], v[48:63]
	ds_read_b128 v[146:149], v135 offset:41504
	ds_read_b128 v[150:153], v135 offset:36928
	v_mfma_f32_32x32x16_bf16 v[16:31], v[158:161], v[142:145], v[16:31]
	ds_read_b128 v[142:145], v134 offset:4640
	s_waitcnt lgkmcnt(3)
	v_mfma_f32_32x32x16_bf16 v[48:63], v[162:165], v[154:157], v[48:63]
	s_waitcnt lgkmcnt(0)
	v_mfma_f32_32x32x16_bf16 v[16:31], v[162:165], v[142:145], v[16:31]
	v_mfma_f32_32x32x16_bf16 v[32:47], v[146:149], v[154:157], v[32:47]
	ds_read_b128 v[154:157], v135 offset:41536
	v_mfma_f32_32x32x16_bf16 v[0:15], v[146:149], v[142:145], v[0:15]
	ds_read_b128 v[142:145], v134 offset:64
	ds_read_b128 v[146:149], v134 offset:4672
	s_waitcnt lgkmcnt(1)
	v_mfma_f32_32x32x16_bf16 v[48:63], v[150:153], v[142:145], v[48:63]
	s_waitcnt lgkmcnt(0)
	v_mfma_f32_32x32x16_bf16 v[16:31], v[150:153], v[146:149], v[16:31]
	ds_read_b128 v[150:153], v135 offset:36960
	v_mfma_f32_32x32x16_bf16 v[32:47], v[154:157], v[142:145], v[32:47]
	ds_read_b128 v[142:145], v134 offset:96
	v_mfma_f32_32x32x16_bf16 v[0:15], v[154:157], v[146:149], v[0:15]
	ds_read_b128 v[154:157], v135 offset:41568
	ds_read_b128 v[146:149], v134 offset:4704
	s_waitcnt lgkmcnt(2)
	v_mfma_f32_32x32x16_bf16 v[48:63], v[150:153], v[142:145], v[48:63]
	s_waitcnt lgkmcnt(0)
	v_mfma_f32_32x32x16_bf16 v[16:31], v[150:153], v[146:149], v[16:31]
	v_mfma_f32_32x32x16_bf16 v[32:47], v[154:157], v[142:145], v[32:47]
	v_mfma_f32_32x32x16_bf16 v[0:15], v[154:157], v[146:149], v[0:15]
	s_setprio 0
	s_cmp_gt_u32 s20, 12
	s_cbranch_scc1 .Lvt_2
	s_waitcnt vmcnt(15)
	ds_write_b128 v132, v[88:91] offset:18432
	s_waitcnt vmcnt(14)
	ds_write_b128 v132, v[92:95] offset:55296
	s_waitcnt vmcnt(13)
	ds_write_b128 v132, v[104:107] offset:23040
	s_waitcnt vmcnt(12)
	ds_write_b128 v132, v[108:111] offset:59904
	s_waitcnt vmcnt(11)
	ds_write_b128 v132, v[112:115] offset:27648
	s_waitcnt vmcnt(10)
	ds_write_b128 v132, v[116:119] offset:64512
	s_waitcnt vmcnt(9)
	ds_write_b128 v132, v[120:123] offset:32256
	s_waitcnt vmcnt(8)
	ds_write_b128 v139, v[124:127] offset:13824
	s_branch .Lvj_2
.Lvt_2:
	s_waitcnt vmcnt(7)
	ds_write_b128 v132, v[88:91] offset:18432
	s_waitcnt vmcnt(6)
	ds_write_b128 v132, v[92:95] offset:55296
	s_waitcnt vmcnt(5)
	ds_write_b128 v132, v[104:107] offset:23040
	s_waitcnt vmcnt(4)
	ds_write_b128 v132, v[108:111] offset:59904
	s_waitcnt vmcnt(3)
	ds_write_b128 v132, v[112:115] offset:27648
	s_waitcnt vmcnt(2)
	ds_write_b128 v132, v[116:119] offset:64512
	s_waitcnt vmcnt(1)
	ds_write_b128 v132, v[120:123] offset:32256
	s_waitcnt vmcnt(0)
	ds_write_b128 v139, v[124:127] offset:13824
.Lvj_2:
	s_waitcnt lgkmcnt(0)
	s_barrier
	s_cbranch_scc1 .LBB0_630
	v_add_u32_e32 v88, 0x180, v141
	v_lshl_add_u64 v[92:93], v[136:137], 0, s[2:3]
	v_add_u32_e32 v104, 0x10180, v141
	v_add_u32_e32 v108, 0x10180, v140
	v_add_u32_e32 v112, 0x20180, v141
	v_add_u32_e32 v116, 0x20180, v140
	v_add_u32_e32 v120, 0x30180, v141
	v_add_u32_e32 v124, 0x30180, v140
	global_load_dwordx4 v[88:91], v88, s[8:9]
	s_nop 0
	global_load_dwordx4 v[92:95], v[92:93], off
	s_nop 0
	global_load_dwordx4 v[104:107], v104, s[8:9]
	s_nop 0
	global_load_dwordx4 v[108:111], v108, s[10:11]
	s_nop 0
	global_load_dwordx4 v[112:115], v112, s[8:9]
	s_nop 0
	global_load_dwordx4 v[116:119], v116, s[10:11]
	s_nop 0
	global_load_dwordx4 v[120:123], v120, s[8:9]
	s_nop 0
	global_load_dwordx4 v[124:127], v124, s[10:11]
.LBB0_630:
	s_setprio 1
	ds_read_b128 v[144:147], v135 offset:59904
	ds_read_b128 v[140:143], v134 offset:23040
	s_waitcnt lgkmcnt(0)
	v_mfma_f32_32x32x16_bf16 v[0:15], v[144:147], v[140:143], v[0:15]
	ds_read_b128 v[148:151], v134 offset:18432
	ds_read_b128 v[152:155], v134 offset:18464
	s_waitcnt lgkmcnt(1)
	v_mfma_f32_32x32x16_bf16 v[32:47], v[144:147], v[148:151], v[32:47]
	ds_read_b128 v[156:159], v135 offset:55296
	ds_read_b128 v[160:163], v135 offset:55328
	s_waitcnt lgkmcnt(1)
	v_mfma_f32_32x32x16_bf16 v[48:63], v[156:159], v[148:151], v[48:63]
	ds_read_b128 v[144:147], v135 offset:59936
	ds_read_b128 v[148:151], v135 offset:55360
	v_mfma_f32_32x32x16_bf16 v[16:31], v[156:159], v[140:143], v[16:31]
	ds_read_b128 v[140:143], v134 offset:23072
	s_waitcnt lgkmcnt(3)
	v_mfma_f32_32x32x16_bf16 v[48:63], v[160:163], v[152:155], v[48:63]
	s_waitcnt lgkmcnt(0)
	v_mfma_f32_32x32x16_bf16 v[16:31], v[160:163], v[140:143], v[16:31]
	v_mfma_f32_32x32x16_bf16 v[32:47], v[144:147], v[152:155], v[32:47]
	ds_read_b128 v[152:155], v135 offset:59968
	v_mfma_f32_32x32x16_bf16 v[0:15], v[144:147], v[140:143], v[0:15]
	ds_read_b128 v[140:143], v134 offset:18496
	ds_read_b128 v[144:147], v134 offset:23104
	s_waitcnt lgkmcnt(1)
	v_mfma_f32_32x32x16_bf16 v[48:63], v[148:151], v[140:143], v[48:63]
	s_waitcnt lgkmcnt(0)
	v_mfma_f32_32x32x16_bf16 v[16:31], v[148:151], v[144:147], v[16:31]
	ds_read_b128 v[148:151], v135 offset:55392
	v_mfma_f32_32x32x16_bf16 v[32:47], v[152:155], v[140:143], v[32:47]
	ds_read_b128 v[140:143], v134 offset:18528
	v_mfma_f32_32x32x16_bf16 v[0:15], v[152:155], v[144:147], v[0:15]
	ds_read_b128 v[152:155], v135 offset:60000
	ds_read_b128 v[144:147], v134 offset:23136
	s_waitcnt lgkmcnt(2)
	v_mfma_f32_32x32x16_bf16 v[48:63], v[148:151], v[140:143], v[48:63]
	s_waitcnt lgkmcnt(0)
	v_mfma_f32_32x32x16_bf16 v[16:31], v[148:151], v[144:147], v[16:31]
	v_mfma_f32_32x32x16_bf16 v[32:47], v[152:155], v[140:143], v[32:47]
	v_mfma_f32_32x32x16_bf16 v[0:15], v[152:155], v[144:147], v[0:15]
	s_setprio 0
	s_andn2_b64 vcc, exec, s[14:15]
	s_cbranch_vccnz .LBB0_625
	s_waitcnt vmcnt(15)
	ds_write_b128 v132, v[64:67]
	s_waitcnt vmcnt(14)
	ds_write_b128 v132, v[68:71] offset:36864
	s_waitcnt vmcnt(13)
	ds_write_b128 v132, v[72:75] offset:4608
	s_waitcnt vmcnt(12)
	ds_write_b128 v132, v[76:79] offset:41472
	s_waitcnt vmcnt(11)
	ds_write_b128 v132, v[80:83] offset:9216
	s_waitcnt vmcnt(10)
	ds_write_b128 v132, v[84:87] offset:46080
	s_waitcnt vmcnt(9)
	ds_write_b128 v132, v[96:99] offset:13824
	s_waitcnt vmcnt(8)
	ds_write_b128 v132, v[100:103] offset:50688
	s_branch .LBB0_625

.LBB0_736:
	s_setprio 1
	ds_read_b128 v[150:153], v133 offset:41472
	ds_read_b128 v[146:149], v132 offset:4608
	s_waitcnt lgkmcnt(0)
	v_mfma_f32_32x32x16_bf16 v[0:15], v[150:153], v[146:149], v[0:15]
	ds_read_b128 v[154:157], v132
	ds_read_b128 v[158:161], v132 offset:32
	s_waitcnt lgkmcnt(1)
	v_mfma_f32_32x32x16_bf16 v[32:47], v[150:153], v[154:157], v[32:47]
	ds_read_b128 v[162:165], v133 offset:36864
	ds_read_b128 v[166:169], v133 offset:36896
	s_waitcnt lgkmcnt(1)
	v_mfma_f32_32x32x16_bf16 v[48:63], v[162:165], v[154:157], v[48:63]
	ds_read_b128 v[150:153], v133 offset:41504
	ds_read_b128 v[154:157], v133 offset:36928
	v_mfma_f32_32x32x16_bf16 v[16:31], v[162:165], v[146:149], v[16:31]
	ds_read_b128 v[146:149], v132 offset:4640
	s_waitcnt lgkmcnt(3)
	v_mfma_f32_32x32x16_bf16 v[48:63], v[166:169], v[158:161], v[48:63]
	s_waitcnt lgkmcnt(0)
	v_mfma_f32_32x32x16_bf16 v[16:31], v[166:169], v[146:149], v[16:31]
	v_mfma_f32_32x32x16_bf16 v[32:47], v[150:153], v[158:161], v[32:47]
	ds_read_b128 v[158:161], v133 offset:41536
	v_mfma_f32_32x32x16_bf16 v[0:15], v[150:153], v[146:149], v[0:15]
	ds_read_b128 v[146:149], v132 offset:64
	ds_read_b128 v[150:153], v132 offset:4672
	s_waitcnt lgkmcnt(1)
	v_mfma_f32_32x32x16_bf16 v[48:63], v[154:157], v[146:149], v[48:63]
	s_waitcnt lgkmcnt(0)
	v_mfma_f32_32x32x16_bf16 v[16:31], v[154:157], v[150:153], v[16:31]
	ds_read_b128 v[154:157], v133 offset:36960
	v_mfma_f32_32x32x16_bf16 v[32:47], v[158:161], v[146:149], v[32:47]
	ds_read_b128 v[146:149], v132 offset:96
	v_mfma_f32_32x32x16_bf16 v[0:15], v[158:161], v[150:153], v[0:15]
	ds_read_b128 v[158:161], v133 offset:41568
	ds_read_b128 v[150:153], v132 offset:4704
	s_waitcnt lgkmcnt(2)
	v_mfma_f32_32x32x16_bf16 v[48:63], v[154:157], v[146:149], v[48:63]
	s_waitcnt lgkmcnt(0)
	v_mfma_f32_32x32x16_bf16 v[16:31], v[154:157], v[150:153], v[16:31]
	v_mfma_f32_32x32x16_bf16 v[32:47], v[158:161], v[146:149], v[32:47]
	v_mfma_f32_32x32x16_bf16 v[0:15], v[158:161], v[150:153], v[0:15]
	s_setprio 0
	s_cmp_gt_u32 s17, 12
	s_cbranch_scc1 .Lvt_3
	s_waitcnt vmcnt(15)
	ds_write_b128 v130, v[92:95] offset:18432
	s_waitcnt vmcnt(14)
	ds_write_b128 v130, v[96:99] offset:55296
	s_waitcnt vmcnt(13)
	ds_write_b128 v130, v[104:107] offset:23040
	s_waitcnt vmcnt(12)
	ds_write_b128 v130, v[108:111] offset:59904
	s_waitcnt vmcnt(11)
	ds_write_b128 v130, v[112:115] offset:27648
	s_waitcnt vmcnt(10)
	ds_write_b128 v130, v[116:119] offset:64512
	s_waitcnt vmcnt(9)
	ds_write_b128 v130, v[120:123] offset:32256
	s_waitcnt vmcnt(8)
	ds_write_b128 v143, v[124:127] offset:13824
	s_branch .Lvj_3
.Lvt_3:
	s_waitcnt vmcnt(7)
	ds_write_b128 v130, v[92:95] offset:18432
	s_waitcnt vmcnt(6)
	ds_write_b128 v130, v[96:99] offset:55296
	s_waitcnt vmcnt(5)
	ds_write_b128 v130, v[104:107] offset:23040
	s_waitcnt vmcnt(4)
	ds_write_b128 v130, v[108:111] offset:59904
	s_waitcnt vmcnt(3)
	ds_write_b128 v130, v[112:115] offset:27648
	s_waitcnt vmcnt(2)
	ds_write_b128 v130, v[116:119] offset:64512
	s_waitcnt vmcnt(1)
	ds_write_b128 v130, v[120:123] offset:32256
	s_waitcnt vmcnt(0)
	ds_write_b128 v143, v[124:127] offset:13824
.Lvj_3:
	s_waitcnt lgkmcnt(0)
	s_barrier
	s_cbranch_scc1 .LBB0_738
	v_add_u32_e32 v92, 0x180, v144
	v_lshl_add_u64 v[96:97], v[140:141], 0, s[2:3]
	v_add_u32_e32 v104, 0x10180, v144
	v_lshl_add_u64 v[108:109], v[138:139], 0, s[2:3]
	v_add_u32_e32 v112, 0x20180, v144
	v_lshl_add_u64 v[116:117], v[136:137], 0, s[2:3]
	v_add_u32_e32 v120, 0x30180, v144
	v_lshl_add_u64 v[124:125], v[134:135], 0, s[2:3]
	global_load_dwordx4 v[92:95], v92, s[0:1]
	s_nop 0
	global_load_dwordx4 v[96:99], v[96:97], off
	s_nop 0
	global_load_dwordx4 v[104:107], v104, s[0:1]
	s_nop 0
	global_load_dwordx4 v[108:111], v[108:109], off
	s_nop 0
	global_load_dwordx4 v[112:115], v112, s[0:1]
	s_nop 0
	global_load_dwordx4 v[116:119], v[116:117], off
	s_nop 0
	global_load_dwordx4 v[120:123], v120, s[0:1]
	s_nop 0
	global_load_dwordx4 v[124:127], v[124:125], off
.LBB0_738:
	s_setprio 1
	ds_read_b128 v[148:151], v133 offset:59904
	ds_read_b128 v[144:147], v132 offset:23040
	s_waitcnt lgkmcnt(0)
	v_mfma_f32_32x32x16_bf16 v[0:15], v[148:151], v[144:147], v[0:15]
	ds_read_b128 v[152:155], v132 offset:18432
	ds_read_b128 v[156:159], v132 offset:18464
	s_waitcnt lgkmcnt(1)
	v_mfma_f32_32x32x16_bf16 v[32:47], v[148:151], v[152:155], v[32:47]
	ds_read_b128 v[160:163], v133 offset:55296
	ds_read_b128 v[164:167], v133 offset:55328
	s_waitcnt lgkmcnt(1)
	v_mfma_f32_32x32x16_bf16 v[48:63], v[160:163], v[152:155], v[48:63]
	ds_read_b128 v[148:151], v133 offset:59936
	ds_read_b128 v[152:155], v133 offset:55360
	v_mfma_f32_32x32x16_bf16 v[16:31], v[160:163], v[144:147], v[16:31]
	ds_read_b128 v[144:147], v132 offset:23072
	s_waitcnt lgkmcnt(3)
	v_mfma_f32_32x32x16_bf16 v[48:63], v[164:167], v[156:159], v[48:63]
	s_waitcnt lgkmcnt(0)
	v_mfma_f32_32x32x16_bf16 v[16:31], v[164:167], v[144:147], v[16:31]
	v_mfma_f32_32x32x16_bf16 v[32:47], v[148:151], v[156:159], v[32:47]
	ds_read_b128 v[156:159], v133 offset:59968
	v_mfma_f32_32x32x16_bf16 v[0:15], v[148:151], v[144:147], v[0:15]
	ds_read_b128 v[144:147], v132 offset:18496
	ds_read_b128 v[148:151], v132 offset:23104
	s_waitcnt lgkmcnt(1)
	v_mfma_f32_32x32x16_bf16 v[48:63], v[152:155], v[144:147], v[48:63]
	s_waitcnt lgkmcnt(0)
	v_mfma_f32_32x32x16_bf16 v[16:31], v[152:155], v[148:151], v[16:31]
	ds_read_b128 v[152:155], v133 offset:55392
	v_mfma_f32_32x32x16_bf16 v[32:47], v[156:159], v[144:147], v[32:47]
	ds_read_b128 v[144:147], v132 offset:18528
	v_mfma_f32_32x32x16_bf16 v[0:15], v[156:159], v[148:151], v[0:15]
	ds_read_b128 v[156:159], v133 offset:60000
	ds_read_b128 v[148:151], v132 offset:23136
	s_waitcnt lgkmcnt(2)
	v_mfma_f32_32x32x16_bf16 v[48:63], v[152:155], v[144:147], v[48:63]
	s_waitcnt lgkmcnt(0)
	v_mfma_f32_32x32x16_bf16 v[16:31], v[152:155], v[148:151], v[16:31]
	v_mfma_f32_32x32x16_bf16 v[32:47], v[156:159], v[144:147], v[32:47]
	v_mfma_f32_32x32x16_bf16 v[0:15], v[156:159], v[148:151], v[0:15]
	s_setprio 0
	s_andn2_b64 vcc, exec, s[20:21]
	s_cbranch_vccnz .LBB0_733
	s_waitcnt vmcnt(15)
	ds_write_b128 v130, v[64:67]
	s_waitcnt vmcnt(14)
	ds_write_b128 v130, v[68:71] offset:36864
	s_waitcnt vmcnt(13)
	ds_write_b128 v130, v[72:75] offset:4608
	s_waitcnt vmcnt(12)
	ds_write_b128 v130, v[76:79] offset:41472
	s_waitcnt vmcnt(11)
	ds_write_b128 v130, v[80:83] offset:9216
	s_waitcnt vmcnt(10)
	ds_write_b128 v130, v[84:87] offset:46080
	s_waitcnt vmcnt(9)
	ds_write_b128 v130, v[88:91] offset:13824
	s_waitcnt vmcnt(8)
	ds_write_b128 v130, v[100:103] offset:50688
	s_branch .LBB0_733

.LBB0_744:
	s_setprio 1
	ds_read_b128 v[150:153], v133 offset:41472
	ds_read_b128 v[146:149], v132 offset:4608
	s_waitcnt lgkmcnt(0)
	v_mfma_f32_32x32x16_bf16 v[0:15], v[150:153], v[146:149], v[0:15]
	ds_read_b128 v[154:157], v132
	ds_read_b128 v[158:161], v132 offset:32
	s_waitcnt lgkmcnt(1)
	v_mfma_f32_32x32x16_bf16 v[32:47], v[150:153], v[154:157], v[32:47]
	ds_read_b128 v[162:165], v133 offset:36864
	ds_read_b128 v[166:169], v133 offset:36896
	s_waitcnt lgkmcnt(1)
	v_mfma_f32_32x32x16_bf16 v[48:63], v[162:165], v[154:157], v[48:63]
	ds_read_b128 v[150:153], v133 offset:41504
	ds_read_b128 v[154:157], v133 offset:36928
	v_mfma_f32_32x32x16_bf16 v[16:31], v[162:165], v[146:149], v[16:31]
	ds_read_b128 v[146:149], v132 offset:4640
	s_waitcnt lgkmcnt(3)
	v_mfma_f32_32x32x16_bf16 v[48:63], v[166:169], v[158:161], v[48:63]
	s_waitcnt lgkmcnt(0)
	v_mfma_f32_32x32x16_bf16 v[16:31], v[166:169], v[146:149], v[16:31]
	v_mfma_f32_32x32x16_bf16 v[32:47], v[150:153], v[158:161], v[32:47]
	ds_read_b128 v[158:161], v133 offset:41536
	v_mfma_f32_32x32x16_bf16 v[0:15], v[150:153], v[146:149], v[0:15]
	ds_read_b128 v[146:149], v132 offset:64
	ds_read_b128 v[150:153], v132 offset:4672
	s_waitcnt lgkmcnt(1)
	v_mfma_f32_32x32x16_bf16 v[48:63], v[154:157], v[146:149], v[48:63]
	s_waitcnt lgkmcnt(0)
	v_mfma_f32_32x32x16_bf16 v[16:31], v[154:157], v[150:153], v[16:31]
	ds_read_b128 v[154:157], v133 offset:36960
	v_mfma_f32_32x32x16_bf16 v[32:47], v[158:161], v[146:149], v[32:47]
	ds_read_b128 v[146:149], v132 offset:96
	v_mfma_f32_32x32x16_bf16 v[0:15], v[158:161], v[150:153], v[0:15]
	ds_read_b128 v[158:161], v133 offset:41568
	ds_read_b128 v[150:153], v132 offset:4704
	s_waitcnt lgkmcnt(2)
	v_mfma_f32_32x32x16_bf16 v[48:63], v[154:157], v[146:149], v[48:63]
	s_waitcnt lgkmcnt(0)
	v_mfma_f32_32x32x16_bf16 v[16:31], v[154:157], v[150:153], v[16:31]
	v_mfma_f32_32x32x16_bf16 v[32:47], v[158:161], v[146:149], v[32:47]
	v_mfma_f32_32x32x16_bf16 v[0:15], v[158:161], v[150:153], v[0:15]
	s_setprio 0
	s_cmp_gt_u32 s17, 12
	s_cbranch_scc1 .Lvt_4
	s_waitcnt vmcnt(12)
	ds_write_b128 v130, v[100:103] offset:18432
	s_waitcnt vmcnt(10)
	ds_write_b128 v130, v[104:107] offset:55296
	s_waitcnt vmcnt(9)
	ds_write_b128 v130, v[116:119] offset:23040
	s_waitcnt vmcnt(12)
	ds_write_b128 v130, v[96:99] offset:59904
	s_waitcnt vmcnt(8)
	ds_write_b128 v130, v[124:127] offset:27648
	s_waitcnt vmcnt(10)
	ds_write_b128 v130, v[108:111] offset:64512
	s_waitcnt vmcnt(9)
	ds_write_b128 v130, v[112:115] offset:32256
	s_waitcnt vmcnt(8)
	ds_write_b128 v144, v[120:123] offset:13824
	s_branch .Lvj_4
.Lvt_4:
	s_waitcnt vmcnt(4)
	ds_write_b128 v130, v[100:103] offset:18432
	s_waitcnt vmcnt(2)
	ds_write_b128 v130, v[104:107] offset:55296
	s_waitcnt vmcnt(1)
	ds_write_b128 v130, v[116:119] offset:23040
	ds_write_b128 v130, v[96:99] offset:59904
	s_waitcnt vmcnt(0)
	ds_write_b128 v130, v[124:127] offset:27648
	ds_write_b128 v130, v[108:111] offset:64512
	ds_write_b128 v130, v[112:115] offset:32256
	ds_write_b128 v144, v[120:123] offset:13824
.Lvj_4:
	s_waitcnt lgkmcnt(0)
	s_barrier
	s_cbranch_scc1 .LBB0_746
	v_add_u32_e32 v98, 0x180, v145
	v_lshl_add_u64 v[96:97], v[140:141], 0, s[2:3]
	global_load_dwordx4 v[100:103], v98, s[0:1]
	global_load_dwordx4 v[104:107], v[96:97], off
	v_add_u32_e32 v98, 0x10180, v145
	v_lshl_add_u64 v[96:97], v[138:139], 0, s[2:3]
	v_add_u32_e32 v110, 0x20180, v145
	v_lshl_add_u64 v[108:109], v[136:137], 0, s[2:3]
	v_add_u32_e32 v112, 0x30180, v145
	v_lshl_add_u64 v[120:121], v[134:135], 0, s[2:3]
	global_load_dwordx4 v[116:119], v98, s[0:1]
	s_nop 0
	global_load_dwordx4 v[96:99], v[96:97], off
	s_nop 0
	global_load_dwordx4 v[124:127], v110, s[0:1]
	s_nop 0
	global_load_dwordx4 v[108:111], v[108:109], off
	s_nop 0
	global_load_dwordx4 v[112:115], v112, s[0:1]
	s_nop 0
	global_load_dwordx4 v[120:123], v[120:121], off
.LBB0_746:
	s_setprio 1
	ds_read_b128 v[150:153], v133 offset:59904
	ds_read_b128 v[146:149], v132 offset:23040
	s_waitcnt lgkmcnt(0)
	v_mfma_f32_32x32x16_bf16 v[0:15], v[150:153], v[146:149], v[0:15]
	ds_read_b128 v[154:157], v132 offset:18432
	ds_read_b128 v[158:161], v132 offset:18464
	s_waitcnt lgkmcnt(1)
	v_mfma_f32_32x32x16_bf16 v[32:47], v[150:153], v[154:157], v[32:47]
	ds_read_b128 v[162:165], v133 offset:55296
	ds_read_b128 v[166:169], v133 offset:55328
	s_waitcnt lgkmcnt(1)
	v_mfma_f32_32x32x16_bf16 v[48:63], v[162:165], v[154:157], v[48:63]
	ds_read_b128 v[150:153], v133 offset:59936
	ds_read_b128 v[154:157], v133 offset:55360
	v_mfma_f32_32x32x16_bf16 v[16:31], v[162:165], v[146:149], v[16:31]
	ds_read_b128 v[146:149], v132 offset:23072
	s_waitcnt lgkmcnt(3)
	v_mfma_f32_32x32x16_bf16 v[48:63], v[166:169], v[158:161], v[48:63]
	s_waitcnt lgkmcnt(0)
	v_mfma_f32_32x32x16_bf16 v[16:31], v[166:169], v[146:149], v[16:31]
	v_mfma_f32_32x32x16_bf16 v[32:47], v[150:153], v[158:161], v[32:47]
	ds_read_b128 v[158:161], v133 offset:59968
	v_mfma_f32_32x32x16_bf16 v[0:15], v[150:153], v[146:149], v[0:15]
	ds_read_b128 v[146:149], v132 offset:18496
	ds_read_b128 v[150:153], v132 offset:23104
	s_waitcnt lgkmcnt(1)
	v_mfma_f32_32x32x16_bf16 v[48:63], v[154:157], v[146:149], v[48:63]
	s_waitcnt lgkmcnt(0)
	v_mfma_f32_32x32x16_bf16 v[16:31], v[154:157], v[150:153], v[16:31]
	ds_read_b128 v[154:157], v133 offset:55392
	v_mfma_f32_32x32x16_bf16 v[32:47], v[158:161], v[146:149], v[32:47]
	ds_read_b128 v[146:149], v132 offset:18528
	v_mfma_f32_32x32x16_bf16 v[0:15], v[158:161], v[150:153], v[0:15]
	ds_read_b128 v[158:161], v133 offset:60000
	ds_read_b128 v[150:153], v132 offset:23136
	s_waitcnt lgkmcnt(2)
	v_mfma_f32_32x32x16_bf16 v[48:63], v[154:157], v[146:149], v[48:63]
	s_waitcnt lgkmcnt(0)
	v_mfma_f32_32x32x16_bf16 v[16:31], v[154:157], v[150:153], v[16:31]
	v_mfma_f32_32x32x16_bf16 v[32:47], v[158:161], v[146:149], v[32:47]
	v_mfma_f32_32x32x16_bf16 v[0:15], v[158:161], v[150:153], v[0:15]
	s_setprio 0
	s_andn2_b64 vcc, exec, s[20:21]
	s_cbranch_vccnz .LBB0_741
	s_waitcnt vmcnt(15)
	ds_write_b128 v130, v[64:67]
	s_waitcnt vmcnt(14)
	ds_write_b128 v130, v[68:71] offset:36864
	s_waitcnt vmcnt(13)
	ds_write_b128 v130, v[72:75] offset:4608
	s_waitcnt vmcnt(12)
	ds_write_b128 v130, v[76:79] offset:41472
	s_waitcnt vmcnt(11)
	ds_write_b128 v130, v[80:83] offset:9216
	s_waitcnt vmcnt(10)
	ds_write_b128 v130, v[84:87] offset:46080
	s_waitcnt vmcnt(9)
	ds_write_b128 v130, v[88:91] offset:13824
	s_waitcnt vmcnt(8)
	ds_write_b128 v130, v[92:95] offset:50688
	s_branch .LBB0_741

.LBB0_789:
	s_setprio 1
	ds_read_b128 v[144:147], v133 offset:41472
	ds_read_b128 v[140:143], v132 offset:4608
	s_waitcnt lgkmcnt(0)
	v_mfma_f32_32x32x16_bf16 v[0:15], v[144:147], v[140:143], v[0:15]
	ds_read_b128 v[148:151], v132
	ds_read_b128 v[152:155], v132 offset:32
	s_waitcnt lgkmcnt(1)
	v_mfma_f32_32x32x16_bf16 v[32:47], v[144:147], v[148:151], v[32:47]
	ds_read_b128 v[156:159], v133 offset:36864
	ds_read_b128 v[160:163], v133 offset:36896
	s_waitcnt lgkmcnt(1)
	v_mfma_f32_32x32x16_bf16 v[48:63], v[156:159], v[148:151], v[48:63]
	ds_read_b128 v[144:147], v133 offset:41504
	ds_read_b128 v[148:151], v133 offset:36928
	v_mfma_f32_32x32x16_bf16 v[16:31], v[156:159], v[140:143], v[16:31]
	ds_read_b128 v[140:143], v132 offset:4640
	s_waitcnt lgkmcnt(3)
	v_mfma_f32_32x32x16_bf16 v[48:63], v[160:163], v[152:155], v[48:63]
	s_waitcnt lgkmcnt(0)
	v_mfma_f32_32x32x16_bf16 v[16:31], v[160:163], v[140:143], v[16:31]
	v_mfma_f32_32x32x16_bf16 v[32:47], v[144:147], v[152:155], v[32:47]
	ds_read_b128 v[152:155], v133 offset:41536
	v_mfma_f32_32x32x16_bf16 v[0:15], v[144:147], v[140:143], v[0:15]
	ds_read_b128 v[140:143], v132 offset:64
	ds_read_b128 v[144:147], v132 offset:4672
	s_waitcnt lgkmcnt(1)
	v_mfma_f32_32x32x16_bf16 v[48:63], v[148:151], v[140:143], v[48:63]
	s_waitcnt lgkmcnt(0)
	v_mfma_f32_32x32x16_bf16 v[16:31], v[148:151], v[144:147], v[16:31]
	ds_read_b128 v[148:151], v133 offset:36960
	v_mfma_f32_32x32x16_bf16 v[32:47], v[152:155], v[140:143], v[32:47]
	ds_read_b128 v[140:143], v132 offset:96
	v_mfma_f32_32x32x16_bf16 v[0:15], v[152:155], v[144:147], v[0:15]
	ds_read_b128 v[152:155], v133 offset:41568
	ds_read_b128 v[144:147], v132 offset:4704
	s_waitcnt lgkmcnt(2)
	v_mfma_f32_32x32x16_bf16 v[48:63], v[148:151], v[140:143], v[48:63]
	s_waitcnt lgkmcnt(0)
	v_mfma_f32_32x32x16_bf16 v[16:31], v[148:151], v[144:147], v[16:31]
	v_mfma_f32_32x32x16_bf16 v[32:47], v[152:155], v[140:143], v[32:47]
	v_mfma_f32_32x32x16_bf16 v[0:15], v[152:155], v[144:147], v[0:15]
	s_setprio 0
	s_cmp_gt_u32 s25, 12
	s_cbranch_scc1 .Lvt_5
	s_waitcnt vmcnt(15)
	ds_write_b128 v130, v[88:91] offset:18432
	s_waitcnt vmcnt(14)
	ds_write_b128 v130, v[92:95] offset:55296
	s_waitcnt vmcnt(13)
	ds_write_b128 v130, v[104:107] offset:23040
	s_waitcnt vmcnt(12)
	ds_write_b128 v130, v[108:111] offset:59904
	s_waitcnt vmcnt(11)
	ds_write_b128 v130, v[112:115] offset:27648
	s_waitcnt vmcnt(10)
	ds_write_b128 v130, v[116:119] offset:64512
	s_waitcnt vmcnt(9)
	ds_write_b128 v130, v[120:123] offset:32256
	s_waitcnt vmcnt(8)
	ds_write_b128 v137, v[124:127] offset:13824
	s_branch .Lvj_5
.Lvt_5:
	s_waitcnt vmcnt(7)
	ds_write_b128 v130, v[88:91] offset:18432
	s_waitcnt vmcnt(6)
	ds_write_b128 v130, v[92:95] offset:55296
	s_waitcnt vmcnt(5)
	ds_write_b128 v130, v[104:107] offset:23040
	s_waitcnt vmcnt(4)
	ds_write_b128 v130, v[108:111] offset:59904
	s_waitcnt vmcnt(3)
	ds_write_b128 v130, v[112:115] offset:27648
	s_waitcnt vmcnt(2)
	ds_write_b128 v130, v[116:119] offset:64512
	s_waitcnt vmcnt(1)
	ds_write_b128 v130, v[120:123] offset:32256
	s_waitcnt vmcnt(0)
	ds_write_b128 v137, v[124:127] offset:13824
.Lvj_5:
	s_waitcnt lgkmcnt(0)
	s_barrier
	s_cbranch_scc1 .LBB0_791
	v_add_u32_e32 v88, 0x180, v139
	v_lshl_add_u64 v[92:93], v[134:135], 0, s[2:3]
	v_add_u32_e32 v104, 0x10180, v139
	v_add_u32_e32 v108, 0x10180, v138
	v_add_u32_e32 v112, 0x20180, v139
	v_add_u32_e32 v116, 0x20180, v138
	v_add_u32_e32 v120, 0x30180, v139
	v_add_u32_e32 v124, 0x30180, v138
	global_load_dwordx4 v[88:91], v88, s[12:13]
	s_nop 0
	global_load_dwordx4 v[92:95], v[92:93], off
	s_nop 0
	global_load_dwordx4 v[104:107], v104, s[12:13]
	s_nop 0
	global_load_dwordx4 v[108:111], v108, s[14:15]
	s_nop 0
	global_load_dwordx4 v[112:115], v112, s[12:13]
	s_nop 0
	global_load_dwordx4 v[116:119], v116, s[14:15]
	s_nop 0
	global_load_dwordx4 v[120:123], v120, s[12:13]
	s_nop 0
	global_load_dwordx4 v[124:127], v124, s[14:15]
.LBB0_791:
	s_setprio 1
	ds_read_b128 v[142:145], v133 offset:59904
	ds_read_b128 v[138:141], v132 offset:23040
	s_waitcnt lgkmcnt(0)
	v_mfma_f32_32x32x16_bf16 v[0:15], v[142:145], v[138:141], v[0:15]
	ds_read_b128 v[146:149], v132 offset:18432
	ds_read_b128 v[150:153], v132 offset:18464
	s_waitcnt lgkmcnt(1)
	v_mfma_f32_32x32x16_bf16 v[32:47], v[142:145], v[146:149], v[32:47]
	ds_read_b128 v[154:157], v133 offset:55296
	ds_read_b128 v[158:161], v133 offset:55328
	s_waitcnt lgkmcnt(1)
	v_mfma_f32_32x32x16_bf16 v[48:63], v[154:157], v[146:149], v[48:63]
	ds_read_b128 v[142:145], v133 offset:59936
	ds_read_b128 v[146:149], v133 offset:55360
	v_mfma_f32_32x32x16_bf16 v[16:31], v[154:157], v[138:141], v[16:31]
	ds_read_b128 v[138:141], v132 offset:23072
	s_waitcnt lgkmcnt(3)
	v_mfma_f32_32x32x16_bf16 v[48:63], v[158:161], v[150:153], v[48:63]
	s_waitcnt lgkmcnt(0)
	v_mfma_f32_32x32x16_bf16 v[16:31], v[158:161], v[138:141], v[16:31]
	v_mfma_f32_32x32x16_bf16 v[32:47], v[142:145], v[150:153], v[32:47]
	ds_read_b128 v[150:153], v133 offset:59968
	v_mfma_f32_32x32x16_bf16 v[0:15], v[142:145], v[138:141], v[0:15]
	ds_read_b128 v[138:141], v132 offset:18496
	ds_read_b128 v[142:145], v132 offset:23104
	s_waitcnt lgkmcnt(1)
	v_mfma_f32_32x32x16_bf16 v[48:63], v[146:149], v[138:141], v[48:63]
	s_waitcnt lgkmcnt(0)
	v_mfma_f32_32x32x16_bf16 v[16:31], v[146:149], v[142:145], v[16:31]
	ds_read_b128 v[146:149], v133 offset:55392
	v_mfma_f32_32x32x16_bf16 v[32:47], v[150:153], v[138:141], v[32:47]
	ds_read_b128 v[138:141], v132 offset:18528
	v_mfma_f32_32x32x16_bf16 v[0:15], v[150:153], v[142:145], v[0:15]
	ds_read_b128 v[150:153], v133 offset:60000
	ds_read_b128 v[142:145], v132 offset:23136
	s_waitcnt lgkmcnt(2)
	v_mfma_f32_32x32x16_bf16 v[48:63], v[146:149], v[138:141], v[48:63]
	s_waitcnt lgkmcnt(0)
	v_mfma_f32_32x32x16_bf16 v[16:31], v[146:149], v[142:145], v[16:31]
	v_mfma_f32_32x32x16_bf16 v[32:47], v[150:153], v[138:141], v[32:47]
	v_mfma_f32_32x32x16_bf16 v[0:15], v[150:153], v[142:145], v[0:15]
	s_setprio 0
	s_andn2_b64 vcc, exec, s[20:21]
	s_cbranch_vccnz .LBB0_786
	s_waitcnt vmcnt(15)
	ds_write_b128 v130, v[64:67]
	s_waitcnt vmcnt(14)
	ds_write_b128 v130, v[68:71] offset:36864
	s_waitcnt vmcnt(13)
	ds_write_b128 v130, v[72:75] offset:4608
	s_waitcnt vmcnt(12)
	ds_write_b128 v130, v[76:79] offset:41472
	s_waitcnt vmcnt(11)
	ds_write_b128 v130, v[80:83] offset:9216
	s_waitcnt vmcnt(10)
	ds_write_b128 v130, v[84:87] offset:46080
	s_waitcnt vmcnt(9)
	ds_write_b128 v130, v[96:99] offset:13824
	s_waitcnt vmcnt(8)
	ds_write_b128 v130, v[100:103] offset:50688
	s_branch .LBB0_786

.LBB0_901:
	s_setprio 1
	ds_read_b128 v[194:197], v184 offset:2560
	ds_read_b128 v[198:201], v184
	ds_read_b128 v[206:209], v190 offset:20480
	ds_read_b128 v[202:205], v184 offset:32
	s_waitcnt lgkmcnt(1)
	v_mfma_f32_32x32x16_bf16 v[112:127], v[198:201], v[206:209], v[112:127]
	ds_read_b128 v[210:213], v190 offset:20512
	v_mfma_f32_32x32x16_bf16 v[80:95], v[194:197], v[206:209], v[80:95]
	ds_read_b128 v[206:209], v190 offset:23040
	s_waitcnt lgkmcnt(0)
	v_mfma_f32_32x32x16_bf16 v[96:111], v[198:201], v[206:209], v[96:111]
	v_mfma_f32_32x32x16_bf16 v[64:79], v[194:197], v[206:209], v[64:79]
	ds_read_b128 v[206:209], v190 offset:25600
	s_waitcnt lgkmcnt(0)
	v_mfma_f32_32x32x16_bf16 v[48:63], v[198:201], v[206:209], v[48:63]
	v_mfma_f32_32x32x16_bf16 v[16:31], v[194:197], v[206:209], v[16:31]
	ds_read_b128 v[206:209], v190 offset:28160
	s_waitcnt lgkmcnt(0)
	v_mfma_f32_32x32x16_bf16 v[32:47], v[198:201], v[206:209], v[32:47]
	ds_read_b128 v[198:201], v190 offset:23072
	v_mfma_f32_32x32x16_bf16 v[0:15], v[194:197], v[206:209], v[0:15]
	ds_read_b128 v[194:197], v184 offset:2592
	v_mfma_f32_32x32x16_bf16 v[112:127], v[202:205], v[210:213], v[112:127]
	s_waitcnt lgkmcnt(0)
	v_mfma_f32_32x32x16_bf16 v[80:95], v[194:197], v[210:213], v[80:95]
	v_mfma_f32_32x32x16_bf16 v[96:111], v[202:205], v[198:201], v[96:111]
	v_mfma_f32_32x32x16_bf16 v[64:79], v[194:197], v[198:201], v[64:79]
	ds_read_b128 v[198:201], v190 offset:25632
	s_waitcnt lgkmcnt(0)
	v_mfma_f32_32x32x16_bf16 v[48:63], v[202:205], v[198:201], v[48:63]
	v_mfma_f32_32x32x16_bf16 v[16:31], v[194:197], v[198:201], v[16:31]
	ds_read_b128 v[198:201], v190 offset:28192
	s_waitcnt lgkmcnt(0)
	v_mfma_f32_32x32x16_bf16 v[32:47], v[202:205], v[198:201], v[32:47]
	v_mfma_f32_32x32x16_bf16 v[0:15], v[194:197], v[198:201], v[0:15]
	s_setprio 0
	s_cmp_gt_u32 s35, 28
	s_cbranch_scc1 .Lvt_6
	s_waitcnt vmcnt(11)
	ds_write_b128 v188, v[148:151] offset:10240
	s_waitcnt vmcnt(10)
	ds_write_b128 v188, v[156:159] offset:15360
	s_waitcnt vmcnt(9)
	ds_write_b128 v188, v[160:163] offset:40960
	s_waitcnt vmcnt(8)
	ds_write_b128 v188, v[164:167] offset:46080
	s_waitcnt vmcnt(7)
	ds_write_b128 v188, v[168:171] offset:51200
	s_waitcnt vmcnt(6)
	ds_write_b128 v188, v[172:175] offset:56320
	s_branch .Lvj_6
.Lvt_6:
	s_waitcnt vmcnt(5)
	ds_write_b128 v188, v[148:151] offset:10240
	s_waitcnt vmcnt(4)
	ds_write_b128 v188, v[156:159] offset:15360
	s_waitcnt vmcnt(3)
	ds_write_b128 v188, v[160:163] offset:40960
	s_waitcnt vmcnt(2)
	ds_write_b128 v188, v[164:167] offset:46080
	s_waitcnt vmcnt(1)
	ds_write_b128 v188, v[168:171] offset:51200
	s_waitcnt vmcnt(0)
	ds_write_b128 v188, v[172:175] offset:56320
.Lvj_6:
	s_waitcnt lgkmcnt(0)
	s_barrier
	s_cbranch_scc1 .LBB0_903
	v_add_u32_e32 v148, 0xc0, v193
	v_add_u32_e32 v156, 0xc0, v192
	v_lshl_add_u64 v[160:161], v[186:187], 0, s[2:3]
	v_add_u32_e32 v164, 0x200c0, v191
	v_add_u32_e32 v168, 0x400c0, v191
	v_add_u32_e32 v172, 0x600c0, v191
	global_load_dwordx4 v[148:151], v148, s[6:7]
	s_nop 0
	global_load_dwordx4 v[156:159], v156, s[6:7]
	s_nop 0
	global_load_dwordx4 v[160:163], v[160:161], off
	s_nop 0
	global_load_dwordx4 v[164:167], v164, s[8:9]
	s_nop 0
	global_load_dwordx4 v[168:171], v168, s[8:9]
	s_nop 0
	global_load_dwordx4 v[172:175], v172, s[8:9]
.LBB0_903:
	s_setprio 1
	ds_read_b128 v[192:195], v184 offset:12800
	ds_read_b128 v[196:199], v184 offset:10240
	ds_read_b128 v[204:207], v190 offset:40960
	ds_read_b128 v[200:203], v184 offset:10272
	s_waitcnt lgkmcnt(1)
	v_mfma_f32_32x32x16_bf16 v[112:127], v[196:199], v[204:207], v[112:127]
	ds_read_b128 v[208:211], v190 offset:40992
	v_mfma_f32_32x32x16_bf16 v[80:95], v[192:195], v[204:207], v[80:95]
	ds_read_b128 v[204:207], v190 offset:43520
	s_waitcnt lgkmcnt(0)
	v_mfma_f32_32x32x16_bf16 v[96:111], v[196:199], v[204:207], v[96:111]
	v_mfma_f32_32x32x16_bf16 v[64:79], v[192:195], v[204:207], v[64:79]
	ds_read_b128 v[204:207], v190 offset:46080
	s_waitcnt lgkmcnt(0)
	v_mfma_f32_32x32x16_bf16 v[48:63], v[196:199], v[204:207], v[48:63]
	v_mfma_f32_32x32x16_bf16 v[16:31], v[192:195], v[204:207], v[16:31]
	ds_read_b128 v[204:207], v190 offset:48640
	s_waitcnt lgkmcnt(0)
	v_mfma_f32_32x32x16_bf16 v[32:47], v[196:199], v[204:207], v[32:47]
	ds_read_b128 v[196:199], v190 offset:43552
	v_mfma_f32_32x32x16_bf16 v[0:15], v[192:195], v[204:207], v[0:15]
	ds_read_b128 v[192:195], v184 offset:12832
	v_mfma_f32_32x32x16_bf16 v[112:127], v[200:203], v[208:211], v[112:127]
	s_waitcnt lgkmcnt(0)
	v_mfma_f32_32x32x16_bf16 v[80:95], v[192:195], v[208:211], v[80:95]
	v_mfma_f32_32x32x16_bf16 v[96:111], v[200:203], v[196:199], v[96:111]
	v_mfma_f32_32x32x16_bf16 v[64:79], v[192:195], v[196:199], v[64:79]
	ds_read_b128 v[196:199], v190 offset:46112
	s_waitcnt lgkmcnt(0)
	v_mfma_f32_32x32x16_bf16 v[48:63], v[200:203], v[196:199], v[48:63]
	v_mfma_f32_32x32x16_bf16 v[16:31], v[192:195], v[196:199], v[16:31]
	ds_read_b128 v[196:199], v190 offset:48672
	s_waitcnt lgkmcnt(0)
	v_mfma_f32_32x32x16_bf16 v[32:47], v[200:203], v[196:199], v[32:47]
	v_mfma_f32_32x32x16_bf16 v[0:15], v[192:195], v[196:199], v[0:15]
	s_setprio 0
	s_andn2_b64 vcc, exec, s[14:15]
	s_cbranch_vccnz .LBB0_898
	s_waitcnt vmcnt(11)
	ds_write_b128 v188, v[128:131]
	s_waitcnt vmcnt(10)
	ds_write_b128 v188, v[132:135] offset:5120
	s_waitcnt vmcnt(9)
	ds_write_b128 v188, v[136:139] offset:20480
	s_waitcnt vmcnt(8)
	ds_write_b128 v188, v[140:143] offset:25600
	s_waitcnt vmcnt(7)
	ds_write_b128 v188, v[144:147] offset:30720
	s_waitcnt vmcnt(6)
	ds_write_b128 v188, v[152:155] offset:35840
	s_branch .LBB0_898

.LBB0_912:
	s_setprio 1
	ds_read_b128 v[152:155], v138 offset:4608
	ds_read_b128 v[156:159], v135 offset:41472
	s_waitcnt lgkmcnt(0)
	v_mfma_f32_32x32x16_bf16 v[0:15], v[152:155], v[156:159], v[0:15]
	ds_read_b128 v[160:163], v138
	ds_read_b128 v[164:167], v138 offset:32
	s_waitcnt lgkmcnt(1)
	v_mfma_f32_32x32x16_bf16 v[32:47], v[160:163], v[156:159], v[32:47]
	ds_read_b128 v[168:171], v135 offset:36864
	ds_read_b128 v[172:175], v135 offset:36896
	s_waitcnt lgkmcnt(1)
	v_mfma_f32_32x32x16_bf16 v[48:63], v[160:163], v[168:171], v[48:63]
	ds_read_b128 v[156:159], v135 offset:41504
	ds_read_b128 v[160:163], v135 offset:36928
	v_mfma_f32_32x32x16_bf16 v[16:31], v[152:155], v[168:171], v[16:31]
	ds_read_b128 v[152:155], v138 offset:4640
	s_waitcnt lgkmcnt(3)
	v_mfma_f32_32x32x16_bf16 v[48:63], v[164:167], v[172:175], v[48:63]
	s_waitcnt lgkmcnt(2)
	v_mfma_f32_32x32x16_bf16 v[32:47], v[164:167], v[156:159], v[32:47]
	ds_read_b128 v[164:167], v135 offset:41536
	s_waitcnt lgkmcnt(1)
	v_mfma_f32_32x32x16_bf16 v[16:31], v[152:155], v[172:175], v[16:31]
	v_mfma_f32_32x32x16_bf16 v[0:15], v[152:155], v[156:159], v[0:15]
	ds_read_b128 v[152:155], v138 offset:64
	ds_read_b128 v[156:159], v138 offset:4672
	s_waitcnt lgkmcnt(1)
	v_mfma_f32_32x32x16_bf16 v[48:63], v[152:155], v[160:163], v[48:63]
	v_mfma_f32_32x32x16_bf16 v[32:47], v[152:155], v[164:167], v[32:47]
	ds_read_b128 v[152:155], v138 offset:96
	s_waitcnt lgkmcnt(1)
	v_mfma_f32_32x32x16_bf16 v[16:31], v[156:159], v[160:163], v[16:31]
	ds_read_b128 v[160:163], v135 offset:36960
	v_mfma_f32_32x32x16_bf16 v[0:15], v[156:159], v[164:167], v[0:15]
	ds_read_b128 v[156:159], v138 offset:4704
	ds_read_b128 v[164:167], v135 offset:41568
	s_waitcnt lgkmcnt(2)
	v_mfma_f32_32x32x16_bf16 v[48:63], v[152:155], v[160:163], v[48:63]
	s_waitcnt lgkmcnt(0)
	v_mfma_f32_32x32x16_bf16 v[32:47], v[152:155], v[164:167], v[32:47]
	v_mfma_f32_32x32x16_bf16 v[16:31], v[156:159], v[160:163], v[16:31]
	v_mfma_f32_32x32x16_bf16 v[0:15], v[156:159], v[164:167], v[0:15]
	s_setprio 0
	s_cmp_gt_u32 s30, 12
	s_cbranch_scc1 .Lvt_7
	s_waitcnt vmcnt(15)
	ds_write_b128 v136, v[88:91] offset:18432
	s_waitcnt vmcnt(14)
	ds_write_b128 v136, v[96:99] offset:55296
	s_waitcnt vmcnt(13)
	ds_write_b128 v136, v[104:107] offset:23040
	s_waitcnt vmcnt(12)
	ds_write_b128 v136, v[108:111] offset:59904
	s_waitcnt vmcnt(11)
	ds_write_b128 v136, v[112:115] offset:27648
	s_waitcnt vmcnt(10)
	ds_write_b128 v136, v[116:119] offset:64512
	s_waitcnt vmcnt(9)
	ds_write_b128 v136, v[120:123] offset:32256
	s_waitcnt vmcnt(8)
	ds_write_b128 v137, v[124:127] offset:13824
	s_branch .Lvj_7
.Lvt_7:
	s_waitcnt vmcnt(7)
	ds_write_b128 v136, v[88:91] offset:18432
	s_waitcnt vmcnt(6)
	ds_write_b128 v136, v[96:99] offset:55296
	s_waitcnt vmcnt(5)
	ds_write_b128 v136, v[104:107] offset:23040
	s_waitcnt vmcnt(4)
	ds_write_b128 v136, v[108:111] offset:59904
	s_waitcnt vmcnt(3)
	ds_write_b128 v136, v[112:115] offset:27648
	s_waitcnt vmcnt(2)
	ds_write_b128 v136, v[116:119] offset:64512
	s_waitcnt vmcnt(1)
	ds_write_b128 v136, v[120:123] offset:32256
	s_waitcnt vmcnt(0)
	ds_write_b128 v137, v[124:127] offset:13824
.Lvj_7:
	s_waitcnt lgkmcnt(0)
	s_barrier
	s_cbranch_scc1 .LBB0_914
	v_add_u32_e32 v88, 0x180, v150
	v_lshl_add_u64 v[96:97], v[146:147], 0, s[2:3]
	v_add_u32_e32 v104, 0x180, v149
	v_lshl_add_u64 v[108:109], v[144:145], 0, s[2:3]
	v_add_u32_e32 v112, 0x180, v148
	v_lshl_add_u64 v[116:117], v[142:143], 0, s[2:3]
	v_add_u32_e32 v120, 0x180, v139
	v_lshl_add_u64 v[124:125], v[140:141], 0, s[2:3]
	global_load_dwordx4 v[88:91], v88, s[6:7]
	s_nop 0
	global_load_dwordx4 v[96:99], v[96:97], off
	s_nop 0
	global_load_dwordx4 v[104:107], v104, s[6:7]
	s_nop 0
	global_load_dwordx4 v[108:111], v[108:109], off
	s_nop 0
	global_load_dwordx4 v[112:115], v112, s[6:7]
	s_nop 0
	global_load_dwordx4 v[116:119], v[116:117], off
	s_nop 0
	global_load_dwordx4 v[120:123], v120, s[6:7]
	s_nop 0
	global_load_dwordx4 v[124:127], v[124:125], off
.LBB0_914:
	s_setprio 1
	ds_read_b128 v[148:151], v138 offset:23040
	ds_read_b128 v[152:155], v135 offset:59904
	s_waitcnt lgkmcnt(0)
	v_mfma_f32_32x32x16_bf16 v[0:15], v[148:151], v[152:155], v[0:15]
	ds_read_b128 v[156:159], v138 offset:18432
	ds_read_b128 v[160:163], v138 offset:18464
	s_waitcnt lgkmcnt(1)
	v_mfma_f32_32x32x16_bf16 v[32:47], v[156:159], v[152:155], v[32:47]
	ds_read_b128 v[164:167], v135 offset:55296
	ds_read_b128 v[168:171], v135 offset:55328
	s_waitcnt lgkmcnt(1)
	v_mfma_f32_32x32x16_bf16 v[48:63], v[156:159], v[164:167], v[48:63]
	ds_read_b128 v[152:155], v135 offset:59936
	ds_read_b128 v[156:159], v135 offset:55360
	v_mfma_f32_32x32x16_bf16 v[16:31], v[148:151], v[164:167], v[16:31]
	ds_read_b128 v[148:151], v138 offset:23072
	s_waitcnt lgkmcnt(3)
	v_mfma_f32_32x32x16_bf16 v[48:63], v[160:163], v[168:171], v[48:63]
	s_waitcnt lgkmcnt(2)
	v_mfma_f32_32x32x16_bf16 v[32:47], v[160:163], v[152:155], v[32:47]
	ds_read_b128 v[160:163], v135 offset:59968
	s_waitcnt lgkmcnt(1)
	v_mfma_f32_32x32x16_bf16 v[16:31], v[148:151], v[168:171], v[16:31]
	v_mfma_f32_32x32x16_bf16 v[0:15], v[148:151], v[152:155], v[0:15]
	ds_read_b128 v[148:151], v138 offset:18496
	ds_read_b128 v[152:155], v138 offset:23104
	s_waitcnt lgkmcnt(1)
	v_mfma_f32_32x32x16_bf16 v[48:63], v[148:151], v[156:159], v[48:63]
	v_mfma_f32_32x32x16_bf16 v[32:47], v[148:151], v[160:163], v[32:47]
	ds_read_b128 v[148:151], v138 offset:18528
	s_waitcnt lgkmcnt(1)
	v_mfma_f32_32x32x16_bf16 v[16:31], v[152:155], v[156:159], v[16:31]
	ds_read_b128 v[156:159], v135 offset:55392
	v_mfma_f32_32x32x16_bf16 v[0:15], v[152:155], v[160:163], v[0:15]
	ds_read_b128 v[152:155], v138 offset:23136
	ds_read_b128 v[160:163], v135 offset:60000
	s_waitcnt lgkmcnt(2)
	v_mfma_f32_32x32x16_bf16 v[48:63], v[148:151], v[156:159], v[48:63]
	s_waitcnt lgkmcnt(0)
	v_mfma_f32_32x32x16_bf16 v[32:47], v[148:151], v[160:163], v[32:47]
	v_mfma_f32_32x32x16_bf16 v[16:31], v[152:155], v[156:159], v[16:31]
	v_mfma_f32_32x32x16_bf16 v[0:15], v[152:155], v[160:163], v[0:15]
	s_setprio 0
	s_andn2_b64 vcc, exec, s[14:15]
	s_cbranch_vccnz .LBB0_909
	s_waitcnt vmcnt(15)
	ds_write_b128 v136, v[64:67]
	s_waitcnt vmcnt(14)
	ds_write_b128 v136, v[68:71] offset:36864
	s_waitcnt vmcnt(13)
	ds_write_b128 v136, v[72:75] offset:4608
	s_waitcnt vmcnt(12)
	ds_write_b128 v136, v[76:79] offset:41472
	s_waitcnt vmcnt(11)
	ds_write_b128 v136, v[80:83] offset:9216
	s_waitcnt vmcnt(10)
	ds_write_b128 v136, v[84:87] offset:46080
	s_waitcnt vmcnt(9)
	ds_write_b128 v136, v[92:95] offset:13824
	s_waitcnt vmcnt(8)
	ds_write_b128 v136, v[100:103] offset:50688
	s_branch .LBB0_909

.LBB0_951:
	s_setprio 1
	ds_read_b128 v[144:147], v131 offset:41472
	ds_read_b128 v[140:143], v132 offset:4608
	s_waitcnt lgkmcnt(0)
	v_mfma_f32_32x32x16_bf16 v[0:15], v[144:147], v[140:143], v[0:15]
	ds_read_b128 v[148:151], v132
	ds_read_b128 v[152:155], v132 offset:32
	s_waitcnt lgkmcnt(1)
	v_mfma_f32_32x32x16_bf16 v[32:47], v[144:147], v[148:151], v[32:47]
	ds_read_b128 v[156:159], v131 offset:36864
	ds_read_b128 v[160:163], v131 offset:36896
	s_waitcnt lgkmcnt(1)
	v_mfma_f32_32x32x16_bf16 v[48:63], v[156:159], v[148:151], v[48:63]
	ds_read_b128 v[144:147], v131 offset:41504
	ds_read_b128 v[148:151], v131 offset:36928
	v_mfma_f32_32x32x16_bf16 v[16:31], v[156:159], v[140:143], v[16:31]
	ds_read_b128 v[140:143], v132 offset:4640
	s_waitcnt lgkmcnt(3)
	v_mfma_f32_32x32x16_bf16 v[48:63], v[160:163], v[152:155], v[48:63]
	s_waitcnt lgkmcnt(0)
	v_mfma_f32_32x32x16_bf16 v[16:31], v[160:163], v[140:143], v[16:31]
	v_mfma_f32_32x32x16_bf16 v[32:47], v[144:147], v[152:155], v[32:47]
	ds_read_b128 v[152:155], v131 offset:41536
	v_mfma_f32_32x32x16_bf16 v[0:15], v[144:147], v[140:143], v[0:15]
	ds_read_b128 v[140:143], v132 offset:64
	ds_read_b128 v[144:147], v132 offset:4672
	s_waitcnt lgkmcnt(1)
	v_mfma_f32_32x32x16_bf16 v[48:63], v[148:151], v[140:143], v[48:63]
	s_waitcnt lgkmcnt(0)
	v_mfma_f32_32x32x16_bf16 v[16:31], v[148:151], v[144:147], v[16:31]
	ds_read_b128 v[148:151], v131 offset:36960
	v_mfma_f32_32x32x16_bf16 v[32:47], v[152:155], v[140:143], v[32:47]
	ds_read_b128 v[140:143], v132 offset:96
	v_mfma_f32_32x32x16_bf16 v[0:15], v[152:155], v[144:147], v[0:15]
	ds_read_b128 v[152:155], v131 offset:41568
	ds_read_b128 v[144:147], v132 offset:4704
	s_waitcnt lgkmcnt(2)
	v_mfma_f32_32x32x16_bf16 v[48:63], v[148:151], v[140:143], v[48:63]
	s_waitcnt lgkmcnt(0)
	v_mfma_f32_32x32x16_bf16 v[16:31], v[148:151], v[144:147], v[16:31]
	v_mfma_f32_32x32x16_bf16 v[32:47], v[152:155], v[140:143], v[32:47]
	v_mfma_f32_32x32x16_bf16 v[0:15], v[152:155], v[144:147], v[0:15]
	s_setprio 0
	s_cmp_gt_u32 s22, 52
	s_cbranch_scc1 .Lvt_8
	s_waitcnt vmcnt(15)
	ds_write_b128 v130, v[96:99] offset:18432
	s_waitcnt vmcnt(14)
	ds_write_b128 v130, v[100:103] offset:55296
	s_waitcnt vmcnt(13)
	ds_write_b128 v130, v[104:107] offset:23040
	s_waitcnt vmcnt(12)
	ds_write_b128 v130, v[108:111] offset:59904
	s_waitcnt vmcnt(11)
	ds_write_b128 v130, v[112:115] offset:27648
	s_waitcnt vmcnt(10)
	ds_write_b128 v130, v[116:119] offset:64512
	s_waitcnt vmcnt(9)
	ds_write_b128 v130, v[120:123] offset:32256
	s_waitcnt vmcnt(8)
	ds_write_b128 v133, v[124:127] offset:13824
	s_branch .Lvj_8
.Lvt_8:
	s_waitcnt vmcnt(7)
	ds_write_b128 v130, v[96:99] offset:18432
	s_waitcnt vmcnt(6)
	ds_write_b128 v130, v[100:103] offset:55296
	s_waitcnt vmcnt(5)
	ds_write_b128 v130, v[104:107] offset:23040
	s_waitcnt vmcnt(4)
	ds_write_b128 v130, v[108:111] offset:59904
	s_waitcnt vmcnt(3)
	ds_write_b128 v130, v[112:115] offset:27648
	s_waitcnt vmcnt(2)
	ds_write_b128 v130, v[116:119] offset:64512
	s_waitcnt vmcnt(1)
	ds_write_b128 v130, v[120:123] offset:32256
	s_waitcnt vmcnt(0)
	ds_write_b128 v133, v[124:127] offset:13824
.Lvj_8:
	s_waitcnt lgkmcnt(0)
	s_barrier
	s_cbranch_scc1 .LBB0_953
	v_add_u32_e32 v96, 0x180, v139
	v_add_u32_e32 v100, 0x180, v138
	v_add_u32_e32 v104, 0x38180, v139
	v_add_u32_e32 v108, 0x38180, v138
	v_add_u32_e32 v112, 0x70180, v139
	v_add_u32_e32 v116, 0x70180, v138
	v_add_u32_e32 v120, 0xa8180, v139
	v_add_u32_e32 v124, 0xa8180, v138
	global_load_dwordx4 v[96:99], v96, s[8:9]
	s_nop 0
	global_load_dwordx4 v[100:103], v100, s[10:11]
	s_nop 0
	global_load_dwordx4 v[104:107], v104, s[8:9]
	s_nop 0
	global_load_dwordx4 v[108:111], v108, s[10:11]
	s_nop 0
	global_load_dwordx4 v[112:115], v112, s[8:9]
	s_nop 0
	global_load_dwordx4 v[116:119], v116, s[10:11]
	s_nop 0
	global_load_dwordx4 v[120:123], v120, s[8:9]
	s_nop 0
	global_load_dwordx4 v[124:127], v124, s[10:11]
.LBB0_953:
	s_setprio 1
	ds_read_b128 v[142:145], v131 offset:59904
	ds_read_b128 v[138:141], v132 offset:23040
	s_waitcnt lgkmcnt(0)
	v_mfma_f32_32x32x16_bf16 v[0:15], v[142:145], v[138:141], v[0:15]
	ds_read_b128 v[146:149], v132 offset:18432
	ds_read_b128 v[150:153], v132 offset:18464
	s_waitcnt lgkmcnt(1)
	v_mfma_f32_32x32x16_bf16 v[32:47], v[142:145], v[146:149], v[32:47]
	ds_read_b128 v[154:157], v131 offset:55296
	ds_read_b128 v[158:161], v131 offset:55328
	s_waitcnt lgkmcnt(1)
	v_mfma_f32_32x32x16_bf16 v[48:63], v[154:157], v[146:149], v[48:63]
	ds_read_b128 v[142:145], v131 offset:59936
	ds_read_b128 v[146:149], v131 offset:55360
	v_mfma_f32_32x32x16_bf16 v[16:31], v[154:157], v[138:141], v[16:31]
	ds_read_b128 v[138:141], v132 offset:23072
	s_waitcnt lgkmcnt(3)
	v_mfma_f32_32x32x16_bf16 v[48:63], v[158:161], v[150:153], v[48:63]
	s_waitcnt lgkmcnt(0)
	v_mfma_f32_32x32x16_bf16 v[16:31], v[158:161], v[138:141], v[16:31]
	v_mfma_f32_32x32x16_bf16 v[32:47], v[142:145], v[150:153], v[32:47]
	ds_read_b128 v[150:153], v131 offset:59968
	v_mfma_f32_32x32x16_bf16 v[0:15], v[142:145], v[138:141], v[0:15]
	ds_read_b128 v[138:141], v132 offset:18496
	ds_read_b128 v[142:145], v132 offset:23104
	s_waitcnt lgkmcnt(1)
	v_mfma_f32_32x32x16_bf16 v[48:63], v[146:149], v[138:141], v[48:63]
	s_waitcnt lgkmcnt(0)
	v_mfma_f32_32x32x16_bf16 v[16:31], v[146:149], v[142:145], v[16:31]
	ds_read_b128 v[146:149], v131 offset:55392
	v_mfma_f32_32x32x16_bf16 v[32:47], v[150:153], v[138:141], v[32:47]
	ds_read_b128 v[138:141], v132 offset:18528
	v_mfma_f32_32x32x16_bf16 v[0:15], v[150:153], v[142:145], v[0:15]
	ds_read_b128 v[150:153], v131 offset:60000
	ds_read_b128 v[142:145], v132 offset:23136
	s_waitcnt lgkmcnt(2)
	v_mfma_f32_32x32x16_bf16 v[48:63], v[146:149], v[138:141], v[48:63]
	s_waitcnt lgkmcnt(0)
	v_mfma_f32_32x32x16_bf16 v[16:31], v[146:149], v[142:145], v[16:31]
	v_mfma_f32_32x32x16_bf16 v[32:47], v[150:153], v[138:141], v[32:47]
	v_mfma_f32_32x32x16_bf16 v[0:15], v[150:153], v[142:145], v[0:15]
	s_setprio 0
	s_andn2_b64 vcc, exec, s[12:13]
	s_cbranch_vccnz .LBB0_948
	s_waitcnt vmcnt(15)
	ds_write_b128 v130, v[64:67]
	s_waitcnt vmcnt(14)
	ds_write_b128 v130, v[68:71] offset:36864
	s_waitcnt vmcnt(13)
	ds_write_b128 v130, v[72:75] offset:4608
	s_waitcnt vmcnt(12)
	ds_write_b128 v130, v[76:79] offset:41472
	s_waitcnt vmcnt(11)
	ds_write_b128 v130, v[80:83] offset:9216
	s_waitcnt vmcnt(10)
	ds_write_b128 v130, v[84:87] offset:46080
	s_waitcnt vmcnt(9)
	ds_write_b128 v130, v[88:91] offset:13824
	s_waitcnt vmcnt(8)
	ds_write_b128 v130, v[92:95] offset:50688
	s_branch .LBB0_948

.LBB0_999:
	s_setprio 1
	ds_read_b128 v[192:195], v180 offset:2560
	ds_read_b128 v[196:199], v180
	ds_read_b128 v[204:207], v188 offset:20480
	ds_read_b128 v[200:203], v180 offset:32
	s_waitcnt lgkmcnt(1)
	v_mfma_f32_32x32x16_bf16 v[112:127], v[196:199], v[204:207], v[112:127]
	ds_read_b128 v[208:211], v188 offset:20512
	v_mfma_f32_32x32x16_bf16 v[80:95], v[192:195], v[204:207], v[80:95]
	ds_read_b128 v[204:207], v188 offset:23040
	s_waitcnt lgkmcnt(0)
	v_mfma_f32_32x32x16_bf16 v[96:111], v[196:199], v[204:207], v[96:111]
	v_mfma_f32_32x32x16_bf16 v[64:79], v[192:195], v[204:207], v[64:79]
	ds_read_b128 v[204:207], v188 offset:25600
	s_waitcnt lgkmcnt(0)
	v_mfma_f32_32x32x16_bf16 v[48:63], v[196:199], v[204:207], v[48:63]
	v_mfma_f32_32x32x16_bf16 v[16:31], v[192:195], v[204:207], v[16:31]
	ds_read_b128 v[204:207], v188 offset:28160
	s_waitcnt lgkmcnt(0)
	v_mfma_f32_32x32x16_bf16 v[32:47], v[196:199], v[204:207], v[32:47]
	ds_read_b128 v[196:199], v188 offset:23072
	v_mfma_f32_32x32x16_bf16 v[0:15], v[192:195], v[204:207], v[0:15]
	ds_read_b128 v[192:195], v180 offset:2592
	v_mfma_f32_32x32x16_bf16 v[112:127], v[200:203], v[208:211], v[112:127]
	s_waitcnt lgkmcnt(0)
	v_mfma_f32_32x32x16_bf16 v[80:95], v[192:195], v[208:211], v[80:95]
	v_mfma_f32_32x32x16_bf16 v[96:111], v[200:203], v[196:199], v[96:111]
	v_mfma_f32_32x32x16_bf16 v[64:79], v[192:195], v[196:199], v[64:79]
	ds_read_b128 v[196:199], v188 offset:25632
	s_waitcnt lgkmcnt(0)
	v_mfma_f32_32x32x16_bf16 v[48:63], v[200:203], v[196:199], v[48:63]
	v_mfma_f32_32x32x16_bf16 v[16:31], v[192:195], v[196:199], v[16:31]
	ds_read_b128 v[196:199], v188 offset:28192
	s_waitcnt lgkmcnt(0)
	v_mfma_f32_32x32x16_bf16 v[32:47], v[200:203], v[196:199], v[32:47]
	v_mfma_f32_32x32x16_bf16 v[0:15], v[192:195], v[196:199], v[0:15]
	s_setprio 0
	s_cmp_gt_u32 s15, 28
	s_cbranch_scc1 .Lvt_9
	s_waitcnt vmcnt(11)
	ds_write_b128 v186, v[148:151] offset:10240
	s_waitcnt vmcnt(10)
	ds_write_b128 v186, v[156:159] offset:15360
	s_waitcnt vmcnt(9)
	ds_write_b128 v186, v[160:163] offset:40960
	s_waitcnt vmcnt(8)
	ds_write_b128 v186, v[164:167] offset:46080
	s_waitcnt vmcnt(7)
	ds_write_b128 v186, v[168:171] offset:51200
	s_waitcnt vmcnt(6)
	ds_write_b128 v186, v[172:175] offset:56320
	s_branch .Lvj_9
.Lvt_9:
	s_waitcnt vmcnt(5)
	ds_write_b128 v186, v[148:151] offset:10240
	s_waitcnt vmcnt(4)
	ds_write_b128 v186, v[156:159] offset:15360
	s_waitcnt vmcnt(3)
	ds_write_b128 v186, v[160:163] offset:40960
	s_waitcnt vmcnt(2)
	ds_write_b128 v186, v[164:167] offset:46080
	s_waitcnt vmcnt(1)
	ds_write_b128 v186, v[168:171] offset:51200
	s_waitcnt vmcnt(0)
	ds_write_b128 v186, v[172:175] offset:56320
.Lvj_9:
	s_waitcnt lgkmcnt(0)
	s_barrier
	s_cbranch_scc1 .LBB0_1001
	v_add_u32_e32 v148, 0xc0, v190
	v_add_u32_e32 v156, 0x200c0, v190
	v_add_u32_e32 v160, 0xc0, v189
	v_add_u32_e32 v164, 0x200c0, v189
	v_add_u32_e32 v168, 0x400c0, v189
	v_add_u32_e32 v172, 0x600c0, v189
	global_load_dwordx4 v[148:151], v148, s[4:5]
	s_nop 0
	global_load_dwordx4 v[156:159], v156, s[4:5]
	s_nop 0
	global_load_dwordx4 v[160:163], v160, s[6:7]
	s_nop 0
	global_load_dwordx4 v[164:167], v164, s[6:7]
	s_nop 0
	global_load_dwordx4 v[168:171], v168, s[6:7]
	s_nop 0
	global_load_dwordx4 v[172:175], v172, s[6:7]
.LBB0_1001:
	s_setprio 1
	ds_read_b128 v[190:193], v180 offset:12800
	ds_read_b128 v[194:197], v180 offset:10240
	ds_read_b128 v[202:205], v188 offset:40960
	ds_read_b128 v[198:201], v180 offset:10272
	s_waitcnt lgkmcnt(1)
	v_mfma_f32_32x32x16_bf16 v[112:127], v[194:197], v[202:205], v[112:127]
	ds_read_b128 v[206:209], v188 offset:40992
	v_mfma_f32_32x32x16_bf16 v[80:95], v[190:193], v[202:205], v[80:95]
	ds_read_b128 v[202:205], v188 offset:43520
	s_waitcnt lgkmcnt(0)
	v_mfma_f32_32x32x16_bf16 v[96:111], v[194:197], v[202:205], v[96:111]
	v_mfma_f32_32x32x16_bf16 v[64:79], v[190:193], v[202:205], v[64:79]
	ds_read_b128 v[202:205], v188 offset:46080
	s_waitcnt lgkmcnt(0)
	v_mfma_f32_32x32x16_bf16 v[48:63], v[194:197], v[202:205], v[48:63]
	v_mfma_f32_32x32x16_bf16 v[16:31], v[190:193], v[202:205], v[16:31]
	ds_read_b128 v[202:205], v188 offset:48640
	s_waitcnt lgkmcnt(0)
	v_mfma_f32_32x32x16_bf16 v[32:47], v[194:197], v[202:205], v[32:47]
	ds_read_b128 v[194:197], v188 offset:43552
	v_mfma_f32_32x32x16_bf16 v[0:15], v[190:193], v[202:205], v[0:15]
	ds_read_b128 v[190:193], v180 offset:12832
	v_mfma_f32_32x32x16_bf16 v[112:127], v[198:201], v[206:209], v[112:127]
	s_waitcnt lgkmcnt(0)
	v_mfma_f32_32x32x16_bf16 v[80:95], v[190:193], v[206:209], v[80:95]
	v_mfma_f32_32x32x16_bf16 v[96:111], v[198:201], v[194:197], v[96:111]
	v_mfma_f32_32x32x16_bf16 v[64:79], v[190:193], v[194:197], v[64:79]
	ds_read_b128 v[194:197], v188 offset:46112
	s_waitcnt lgkmcnt(0)
	v_mfma_f32_32x32x16_bf16 v[48:63], v[198:201], v[194:197], v[48:63]
	v_mfma_f32_32x32x16_bf16 v[16:31], v[190:193], v[194:197], v[16:31]
	ds_read_b128 v[194:197], v188 offset:48672
	s_waitcnt lgkmcnt(0)
	v_mfma_f32_32x32x16_bf16 v[32:47], v[198:201], v[194:197], v[32:47]
	v_mfma_f32_32x32x16_bf16 v[0:15], v[190:193], v[194:197], v[0:15]
	s_setprio 0
	s_andn2_b64 vcc, exec, s[8:9]
	s_cbranch_vccnz .LBB0_996
	s_waitcnt vmcnt(11)
	ds_write_b128 v186, v[128:131]
	s_waitcnt vmcnt(10)
	ds_write_b128 v186, v[132:135] offset:5120
	s_waitcnt vmcnt(9)
	ds_write_b128 v186, v[136:139] offset:20480
	s_waitcnt vmcnt(8)
	ds_write_b128 v186, v[140:143] offset:25600
	s_waitcnt vmcnt(7)
	ds_write_b128 v186, v[144:147] offset:30720
	s_waitcnt vmcnt(6)
	ds_write_b128 v186, v[152:155] offset:35840
	s_branch .LBB0_996

.LBB0_1012:
	s_setprio 1
	ds_read_b128 v[140:143], v132 offset:4608
	ds_read_b128 v[144:147], v131 offset:41472
	s_waitcnt lgkmcnt(0)
	v_mfma_f32_32x32x16_bf16 v[0:15], v[140:143], v[144:147], v[0:15]
	ds_read_b128 v[148:151], v132
	ds_read_b128 v[152:155], v132 offset:32
	s_waitcnt lgkmcnt(1)
	v_mfma_f32_32x32x16_bf16 v[32:47], v[148:151], v[144:147], v[32:47]
	ds_read_b128 v[156:159], v131 offset:36864
	ds_read_b128 v[160:163], v131 offset:36896
	s_waitcnt lgkmcnt(1)
	v_mfma_f32_32x32x16_bf16 v[48:63], v[148:151], v[156:159], v[48:63]
	ds_read_b128 v[144:147], v131 offset:41504
	ds_read_b128 v[148:151], v131 offset:36928
	v_mfma_f32_32x32x16_bf16 v[16:31], v[140:143], v[156:159], v[16:31]
	ds_read_b128 v[140:143], v132 offset:4640
	s_waitcnt lgkmcnt(3)
	v_mfma_f32_32x32x16_bf16 v[48:63], v[152:155], v[160:163], v[48:63]
	s_waitcnt lgkmcnt(2)
	v_mfma_f32_32x32x16_bf16 v[32:47], v[152:155], v[144:147], v[32:47]
	ds_read_b128 v[152:155], v131 offset:41536
	s_waitcnt lgkmcnt(1)
	v_mfma_f32_32x32x16_bf16 v[16:31], v[140:143], v[160:163], v[16:31]
	v_mfma_f32_32x32x16_bf16 v[0:15], v[140:143], v[144:147], v[0:15]
	ds_read_b128 v[140:143], v132 offset:64
	ds_read_b128 v[144:147], v132 offset:4672
	s_waitcnt lgkmcnt(1)
	v_mfma_f32_32x32x16_bf16 v[48:63], v[140:143], v[148:151], v[48:63]
	v_mfma_f32_32x32x16_bf16 v[32:47], v[140:143], v[152:155], v[32:47]
	ds_read_b128 v[140:143], v132 offset:96
	s_waitcnt lgkmcnt(1)
	v_mfma_f32_32x32x16_bf16 v[16:31], v[144:147], v[148:151], v[16:31]
	ds_read_b128 v[148:151], v131 offset:36960
	v_mfma_f32_32x32x16_bf16 v[0:15], v[144:147], v[152:155], v[0:15]
	ds_read_b128 v[144:147], v132 offset:4704
	ds_read_b128 v[152:155], v131 offset:41568
	s_waitcnt lgkmcnt(2)
	v_mfma_f32_32x32x16_bf16 v[48:63], v[140:143], v[148:151], v[48:63]
	s_waitcnt lgkmcnt(0)
	v_mfma_f32_32x32x16_bf16 v[32:47], v[140:143], v[152:155], v[32:47]
	v_mfma_f32_32x32x16_bf16 v[16:31], v[144:147], v[148:151], v[16:31]
	v_mfma_f32_32x32x16_bf16 v[0:15], v[144:147], v[152:155], v[0:15]
	s_setprio 0
	s_cmp_gt_u32 s14, 12
	s_cbranch_scc1 .Lvt_10
	s_waitcnt vmcnt(15)
	ds_write_b128 v130, v[96:99] offset:18432
	s_waitcnt vmcnt(14)
	ds_write_b128 v130, v[100:103] offset:55296
	s_waitcnt vmcnt(13)
	ds_write_b128 v130, v[104:107] offset:23040
	s_waitcnt vmcnt(12)
	ds_write_b128 v130, v[108:111] offset:59904
	s_waitcnt vmcnt(11)
	ds_write_b128 v130, v[112:115] offset:27648
	s_waitcnt vmcnt(10)
	ds_write_b128 v130, v[116:119] offset:64512
	s_waitcnt vmcnt(9)
	ds_write_b128 v130, v[120:123] offset:32256
	s_waitcnt vmcnt(8)
	ds_write_b128 v133, v[124:127] offset:13824
	s_branch .Lvj_10

.Lvj_10:
	s_waitcnt lgkmcnt(0)
	s_barrier
	s_cbranch_scc1 .LBB0_1014
	v_add_u32_e32 v96, 0x180, v139
	v_add_u32_e32 v100, 0x180, v138
	v_add_u32_e32 v104, 0x10180, v139
	v_add_u32_e32 v108, 0x10180, v138
	v_add_u32_e32 v112, 0x20180, v139
	v_add_u32_e32 v116, 0x20180, v138
	v_add_u32_e32 v120, 0x30180, v139
	v_add_u32_e32 v124, 0x30180, v138
	global_load_dwordx4 v[96:99], v96, s[4:5]
	s_nop 0
	global_load_dwordx4 v[100:103], v100, s[6:7]
	s_nop 0
	global_load_dwordx4 v[104:107], v104, s[4:5]
	s_nop 0
	global_load_dwordx4 v[108:111], v108, s[6:7]
	s_nop 0
	global_load_dwordx4 v[112:115], v112, s[4:5]
	s_nop 0
	global_load_dwordx4 v[116:119], v116, s[6:7]
	s_nop 0
	global_load_dwordx4 v[120:123], v120, s[4:5]
	s_nop 0
	global_load_dwordx4 v[124:127], v124, s[6:7]
.LBB0_1014:
	s_setprio 1
	ds_read_b128 v[138:141], v132 offset:23040
	ds_read_b128 v[142:145], v131 offset:59904
	s_waitcnt lgkmcnt(0)
	v_mfma_f32_32x32x16_bf16 v[0:15], v[138:141], v[142:145], v[0:15]
	ds_read_b128 v[146:149], v132 offset:18432
	ds_read_b128 v[150:153], v132 offset:18464
	s_waitcnt lgkmcnt(1)
	v_mfma_f32_32x32x16_bf16 v[32:47], v[146:149], v[142:145], v[32:47]
	ds_read_b128 v[154:157], v131 offset:55296
	ds_read_b128 v[158:161], v131 offset:55328
	s_waitcnt lgkmcnt(1)
	v_mfma_f32_32x32x16_bf16 v[48:63], v[146:149], v[154:157], v[48:63]
	ds_read_b128 v[142:145], v131 offset:59936
	ds_read_b128 v[146:149], v131 offset:55360
	v_mfma_f32_32x32x16_bf16 v[16:31], v[138:141], v[154:157], v[16:31]
	ds_read_b128 v[138:141], v132 offset:23072
	s_waitcnt lgkmcnt(3)
	v_mfma_f32_32x32x16_bf16 v[48:63], v[150:153], v[158:161], v[48:63]
	s_waitcnt lgkmcnt(2)
	v_mfma_f32_32x32x16_bf16 v[32:47], v[150:153], v[142:145], v[32:47]
	ds_read_b128 v[150:153], v131 offset:59968
	s_waitcnt lgkmcnt(1)
	v_mfma_f32_32x32x16_bf16 v[16:31], v[138:141], v[158:161], v[16:31]
	v_mfma_f32_32x32x16_bf16 v[0:15], v[138:141], v[142:145], v[0:15]
	ds_read_b128 v[138:141], v132 offset:18496
	ds_read_b128 v[142:145], v132 offset:23104
	s_waitcnt lgkmcnt(1)
	v_mfma_f32_32x32x16_bf16 v[48:63], v[138:141], v[146:149], v[48:63]
	v_mfma_f32_32x32x16_bf16 v[32:47], v[138:141], v[150:153], v[32:47]
	ds_read_b128 v[138:141], v132 offset:18528
	s_waitcnt lgkmcnt(1)
	v_mfma_f32_32x32x16_bf16 v[16:31], v[142:145], v[146:149], v[16:31]
	ds_read_b128 v[146:149], v131 offset:55392
	v_mfma_f32_32x32x16_bf16 v[0:15], v[142:145], v[150:153], v[0:15]
	ds_read_b128 v[142:145], v132 offset:23136
	ds_read_b128 v[150:153], v131 offset:60000
	s_waitcnt lgkmcnt(2)
	v_mfma_f32_32x32x16_bf16 v[48:63], v[138:141], v[146:149], v[48:63]
	s_waitcnt lgkmcnt(0)
	v_mfma_f32_32x32x16_bf16 v[32:47], v[138:141], v[150:153], v[32:47]
	v_mfma_f32_32x32x16_bf16 v[16:31], v[142:145], v[146:149], v[16:31]
	v_mfma_f32_32x32x16_bf16 v[0:15], v[142:145], v[150:153], v[0:15]
	s_setprio 0
	s_andn2_b64 vcc, exec, s[8:9]
	s_cbranch_vccnz .LBB0_1009
	s_waitcnt vmcnt(15)
	ds_write_b128 v130, v[64:67]
	s_waitcnt vmcnt(14)
	ds_write_b128 v130, v[68:71] offset:36864
	s_waitcnt vmcnt(13)
	ds_write_b128 v130, v[72:75] offset:4608
	s_waitcnt vmcnt(12)
	ds_write_b128 v130, v[76:79] offset:41472
	s_waitcnt vmcnt(11)
	ds_write_b128 v130, v[80:83] offset:9216
	s_waitcnt vmcnt(10)
	ds_write_b128 v130, v[84:87] offset:46080
	s_waitcnt vmcnt(9)
	ds_write_b128 v130, v[88:91] offset:13824
	s_waitcnt vmcnt(8)
	ds_write_b128 v130, v[92:95] offset:50688
	s_branch .LBB0_1009

.LBB0_1052:
	s_setprio 1
	ds_read_b128 v[144:147], v133 offset:41472
	ds_read_b128 v[140:143], v132 offset:4608
	s_waitcnt lgkmcnt(0)
	v_mfma_f32_32x32x16_bf16 v[0:15], v[144:147], v[140:143], v[0:15]
	ds_read_b128 v[148:151], v132
	ds_read_b128 v[152:155], v132 offset:32
	s_waitcnt lgkmcnt(1)
	v_mfma_f32_32x32x16_bf16 v[32:47], v[144:147], v[148:151], v[32:47]
	ds_read_b128 v[156:159], v133 offset:36864
	ds_read_b128 v[160:163], v133 offset:36896
	s_waitcnt lgkmcnt(1)
	v_mfma_f32_32x32x16_bf16 v[48:63], v[156:159], v[148:151], v[48:63]
	ds_read_b128 v[144:147], v133 offset:41504
	ds_read_b128 v[148:151], v133 offset:36928
	v_mfma_f32_32x32x16_bf16 v[16:31], v[156:159], v[140:143], v[16:31]
	ds_read_b128 v[140:143], v132 offset:4640
	s_waitcnt lgkmcnt(3)
	v_mfma_f32_32x32x16_bf16 v[48:63], v[160:163], v[152:155], v[48:63]
	s_waitcnt lgkmcnt(0)
	v_mfma_f32_32x32x16_bf16 v[16:31], v[160:163], v[140:143], v[16:31]
	v_mfma_f32_32x32x16_bf16 v[32:47], v[144:147], v[152:155], v[32:47]
	ds_read_b128 v[152:155], v133 offset:41536
	v_mfma_f32_32x32x16_bf16 v[0:15], v[144:147], v[140:143], v[0:15]
	ds_read_b128 v[140:143], v132 offset:64
	ds_read_b128 v[144:147], v132 offset:4672
	s_waitcnt lgkmcnt(1)
	v_mfma_f32_32x32x16_bf16 v[48:63], v[148:151], v[140:143], v[48:63]
	s_waitcnt lgkmcnt(0)
	v_mfma_f32_32x32x16_bf16 v[16:31], v[148:151], v[144:147], v[16:31]
	ds_read_b128 v[148:151], v133 offset:36960
	v_mfma_f32_32x32x16_bf16 v[32:47], v[152:155], v[140:143], v[32:47]
	ds_read_b128 v[140:143], v132 offset:96
	v_mfma_f32_32x32x16_bf16 v[0:15], v[152:155], v[144:147], v[0:15]
	ds_read_b128 v[152:155], v133 offset:41568
	ds_read_b128 v[144:147], v132 offset:4704
	s_waitcnt lgkmcnt(2)
	v_mfma_f32_32x32x16_bf16 v[48:63], v[148:151], v[140:143], v[48:63]
	s_waitcnt lgkmcnt(0)
	v_mfma_f32_32x32x16_bf16 v[16:31], v[148:151], v[144:147], v[16:31]
	v_mfma_f32_32x32x16_bf16 v[32:47], v[152:155], v[140:143], v[32:47]
	v_mfma_f32_32x32x16_bf16 v[0:15], v[152:155], v[144:147], v[0:15]
	s_setprio 0
	s_cmp_gt_u32 s15, 40
	s_cbranch_scc1 .Lvt_11
	s_waitcnt vmcnt(15)
	ds_write_b128 v130, v[88:91] offset:18432
	s_waitcnt vmcnt(14)
	ds_write_b128 v130, v[96:99] offset:55296
	s_waitcnt vmcnt(13)
	ds_write_b128 v130, v[104:107] offset:23040
	s_waitcnt vmcnt(12)
	ds_write_b128 v130, v[108:111] offset:59904
	s_waitcnt vmcnt(11)
	ds_write_b128 v130, v[112:115] offset:27648
	s_waitcnt vmcnt(10)
	ds_write_b128 v130, v[116:119] offset:64512
	s_waitcnt vmcnt(9)
	ds_write_b128 v130, v[120:123] offset:32256
	s_waitcnt vmcnt(8)
	ds_write_b128 v137, v[124:127] offset:13824
	s_branch .Lvj_11
.Lvt_11:
	s_waitcnt vmcnt(7)
	ds_write_b128 v130, v[88:91] offset:18432
	s_waitcnt vmcnt(6)
	ds_write_b128 v130, v[96:99] offset:55296
	s_waitcnt vmcnt(5)
	ds_write_b128 v130, v[104:107] offset:23040
	s_waitcnt vmcnt(4)
	ds_write_b128 v130, v[108:111] offset:59904
	s_waitcnt vmcnt(3)
	ds_write_b128 v130, v[112:115] offset:27648
	s_waitcnt vmcnt(2)
	ds_write_b128 v130, v[116:119] offset:64512
	s_waitcnt vmcnt(1)
	ds_write_b128 v130, v[120:123] offset:32256
	s_waitcnt vmcnt(0)
	ds_write_b128 v137, v[124:127] offset:13824
.Lvj_11:
	s_waitcnt lgkmcnt(0)
	s_barrier
	s_cbranch_scc1 .LBB0_1054
	v_add_u32_e32 v88, 0x180, v139
	v_add_u32_e32 v96, 0x180, v138
	v_add_u32_e32 v104, 0x2c180, v139
	v_add_u32_e32 v108, 0x2c180, v138
	v_add_u32_e32 v112, 0x58180, v139
	v_add_u32_e32 v116, 0x58180, v138
	v_add_u32_e32 v120, 0x84180, v139
	v_add_u32_e32 v124, 0x84180, v138
	global_load_dwordx4 v[88:91], v88, s[0:1]
	s_nop 0
	global_load_dwordx4 v[96:99], v96, s[8:9]
	s_nop 0
	global_load_dwordx4 v[104:107], v104, s[0:1]
	s_nop 0
	global_load_dwordx4 v[108:111], v108, s[8:9]
	s_nop 0
	global_load_dwordx4 v[112:115], v112, s[0:1]
	s_nop 0
	global_load_dwordx4 v[116:119], v116, s[8:9]
	s_nop 0
	global_load_dwordx4 v[120:123], v120, s[0:1]
	s_nop 0
	global_load_dwordx4 v[124:127], v124, s[8:9]
.LBB0_1054:
	s_setprio 1
	ds_read_b128 v[142:145], v133 offset:59904
	ds_read_b128 v[138:141], v132 offset:23040
	s_waitcnt lgkmcnt(0)
	v_mfma_f32_32x32x16_bf16 v[0:15], v[142:145], v[138:141], v[0:15]
	ds_read_b128 v[146:149], v132 offset:18432
	ds_read_b128 v[150:153], v132 offset:18464
	s_waitcnt lgkmcnt(1)
	v_mfma_f32_32x32x16_bf16 v[32:47], v[142:145], v[146:149], v[32:47]
	ds_read_b128 v[154:157], v133 offset:55296
	ds_read_b128 v[158:161], v133 offset:55328
	s_waitcnt lgkmcnt(1)
	v_mfma_f32_32x32x16_bf16 v[48:63], v[154:157], v[146:149], v[48:63]
	ds_read_b128 v[142:145], v133 offset:59936
	ds_read_b128 v[146:149], v133 offset:55360
	v_mfma_f32_32x32x16_bf16 v[16:31], v[154:157], v[138:141], v[16:31]
	ds_read_b128 v[138:141], v132 offset:23072
	s_waitcnt lgkmcnt(3)
	v_mfma_f32_32x32x16_bf16 v[48:63], v[158:161], v[150:153], v[48:63]
	s_waitcnt lgkmcnt(0)
	v_mfma_f32_32x32x16_bf16 v[16:31], v[158:161], v[138:141], v[16:31]
	v_mfma_f32_32x32x16_bf16 v[32:47], v[142:145], v[150:153], v[32:47]
	ds_read_b128 v[150:153], v133 offset:59968
	v_mfma_f32_32x32x16_bf16 v[0:15], v[142:145], v[138:141], v[0:15]
	ds_read_b128 v[138:141], v132 offset:18496
	ds_read_b128 v[142:145], v132 offset:23104
	s_waitcnt lgkmcnt(1)
	v_mfma_f32_32x32x16_bf16 v[48:63], v[146:149], v[138:141], v[48:63]
	s_waitcnt lgkmcnt(0)
	v_mfma_f32_32x32x16_bf16 v[16:31], v[146:149], v[142:145], v[16:31]
	ds_read_b128 v[146:149], v133 offset:55392
	v_mfma_f32_32x32x16_bf16 v[32:47], v[150:153], v[138:141], v[32:47]
	ds_read_b128 v[138:141], v132 offset:18528
	v_mfma_f32_32x32x16_bf16 v[0:15], v[150:153], v[142:145], v[0:15]
	ds_read_b128 v[150:153], v133 offset:60000
	ds_read_b128 v[142:145], v132 offset:23136
	s_waitcnt lgkmcnt(2)
	v_mfma_f32_32x32x16_bf16 v[48:63], v[146:149], v[138:141], v[48:63]
	s_waitcnt lgkmcnt(0)
	v_mfma_f32_32x32x16_bf16 v[16:31], v[146:149], v[142:145], v[16:31]
	v_mfma_f32_32x32x16_bf16 v[32:47], v[150:153], v[138:141], v[32:47]
	v_mfma_f32_32x32x16_bf16 v[0:15], v[150:153], v[142:145], v[0:15]
	s_setprio 0
	s_andn2_b64 vcc, exec, s[10:11]
	s_cbranch_vccnz .LBB0_1049
	s_waitcnt vmcnt(15)
	ds_write_b128 v130, v[64:67]
	s_waitcnt vmcnt(14)
	ds_write_b128 v130, v[68:71] offset:36864
	s_waitcnt vmcnt(13)
	ds_write_b128 v130, v[72:75] offset:4608
	s_waitcnt vmcnt(12)
	ds_write_b128 v130, v[76:79] offset:41472
	s_waitcnt vmcnt(11)
	ds_write_b128 v130, v[80:83] offset:9216
	s_waitcnt vmcnt(10)
	ds_write_b128 v130, v[84:87] offset:46080
	s_waitcnt vmcnt(9)
	ds_write_b128 v130, v[92:95] offset:13824
	s_waitcnt vmcnt(8)
	ds_write_b128 v130, v[100:103] offset:50688
	s_branch .LBB0_1049
